# GEMM K loops: first two-tile step peeled with C=0 MFMAs, accumulator zero-fill removed
# baseline (speedup 1.0000x reference)
; #define PG8_STAGE(bufoff, gbase, voff) do { _Pragma("unroll") for (int _i = 0; _i < 2; ++_i) \
;         __builtin_amdgcn_global_load_lds((const unsigned*)((const char*)(gbase) + (voff)[_i]), (LAS unsigned*)(lds + (bufoff) + ldsw + _i * 8192), 16, 0, 0); } while (0)
; #define PG8_LDA(dst, b, h) do { _Pragma("unroll") for (int m = 0; m < 4; ++m) _Pragma("unroll") for (int k = 0; k < 2; ++k) dst[m][k] = *(const LAS bf16x8*)(lds + PG8_SA(b, h) + aoff + m * 2048 + k * 1024); } while (0)
; #define PG8_LDB(dst, b, h) do { _Pragma("unroll") for (int n = 0; n < 2; ++n) _Pragma("unroll") for (int k = 0; k < 2; ++k) dst[n][k] = *(const LAS bf16x8*)(lds + PG8_SB(b, h) + boff + n * 2048 + k * 1024); } while (0)
; #define PG8_MMA(ai, bj, At, Bt) do { __builtin_amdgcn_s_setprio(1); _Pragma("unroll") for (int m = 0; m < 4; ++m) _Pragma("unroll") for (int n = 0; n < 2; ++n) _Pragma("unroll") for (int k = 0; k < 2; ++k) \
;         acc[ai][bj][m][n] = __builtin_amdgcn_mfma_f32_16x16x32_bf16(Bt[n][k], At[m][k], acc[ai][bj][m][n], 0, 0, 0); __builtin_amdgcn_s_setprio(0); } while (0)
; #define PG8_WAIT_V(n) asm volatile("s_waitcnt vmcnt(" #n ")" ::: "memory")
; #define PG8_WAIT_L(n) asm volatile("s_waitcnt lgkmcnt(" #n ")" ::: "memory")
; #define PG8_BAR __builtin_amdgcn_s_barrier()
; #define PG8_SCHED __builtin_amdgcn_sched_barrier(0)
; template <class Epi>
; __device__ __forceinline__ void gemm_phase(LAS unsigned char* lds, const Gemm g, const Sched& S, const Epi& E, const int tid) {
;     ...
;         for (int t = 0; t < nt; t += 2) {
;             const bool last = (t == nt - 2);
;             const char* a1 = cA + (size_t)(t + 1) * kstep;
;             const char* a2 = last ? nA : cA + (size_t)(t + 2) * kstep; const char* b2 = last ? nB : cB + (size_t)(t + 2) * kstep;
;             const char* a3 = a2 + kstep; const char* b3 = b2 + kstep;
;             PG8_LDB(B0, 0, 0); PG8_LDB(B1, 0, 1); PG8_SCHED; PG8_LDA(At, 0, 0); PG8_STAGE(PG8_SA(1, 1), a1 + hA, voffA);
;             PG8_WAIT_V(8); PG8_WAIT_L(0); PG8_BAR; PG8_MMA(0, 0, At, B0); PG8_MMA(0, 1, At, B1); PG8_BAR; PG8_SCHED;
;             PG8_LDA(At, 0, 1); PG8_STAGE(PG8_SB(0, 0), b2, voffB); PG8_STAGE(PG8_SB(0, 1), b2 + hB, voffB); PG8_STAGE(PG8_SA(0, 0), a2, voffA);
.LBB0_332:
	s_add_u32 s10, s10, 0x40080
	s_addc_u32 s11, s11, 0
	s_add_u32 s9, s74, 0x100
	s_addc_u32 s19, s75, 0
	s_mov_b32 s21, -2
	s_add_u32 s35, s10, 0xfffc0080
	s_addc_u32 s37, s11, -1
	s_add_i32 vcc_lo, 0, 0x10000
	s_cmp_eq_u32 s21, 12
	s_cselect_b32 s77, s23, s37
	s_cselect_b32 s76, s22, s35
	s_cselect_b32 s75, s73, s19
	s_cselect_b32 s74, s72, s9
	s_add_i32 s35, 0, 0x14000
	v_add_u32_e32 v156, vcc_lo, v145
	v_add_u32_e32 v172, s35, v145
	ds_read_b128 v[140:143], v156
	ds_read_b128 v[148:151], v156 offset:1024
	ds_read_b128 v[152:155], v156 offset:2048
	ds_read_b128 v[156:159], v156 offset:3072
	ds_read_b128 v[160:163], v172
	ds_read_b128 v[164:167], v172 offset:1024
	ds_read_b128 v[168:171], v172 offset:2048
	ds_read_b128 v[172:175], v172 offset:3072
	v_lshl_add_u64 v[190:191], s[10:11], 0, v[136:137]
	s_add_i32 m0, s13, 0xc000
	ds_read_b128 v[178:181], v147
	ds_read_b128 v[182:185], v147 offset:1024
	ds_read_b128 v[186:189], v147 offset:2048
	ds_read_b128 v[194:197], v147 offset:3072
	ds_read_b128 v[198:201], v147 offset:4096
	ds_read_b128 v[202:205], v147 offset:5120
	ds_read_b128 v[206:209], v147 offset:6144
	ds_read_b128 v[210:213], v147 offset:7168
	global_load_lds_dwordx4 v[190:191], off
	v_lshl_add_u64 v[190:191], s[10:11], 0, v[138:139]
	s_add_i32 m0, s13, 0xe000
	s_nop 0
	global_load_lds_dwordx4 v[190:191], off
	s_waitcnt vmcnt(8)
	s_waitcnt lgkmcnt(0)
	s_barrier
	s_setprio 1
	s_waitcnt lgkmcnt(0)
	v_mfma_f32_16x16x32_bf16 v[124:127], v[140:143], v[178:181], 0
	v_mfma_f32_16x16x32_bf16 v[120:123], v[152:155], v[178:181], 0
	v_mfma_f32_16x16x32_bf16 v[116:119], v[140:143], v[186:189], 0
	v_mfma_f32_16x16x32_bf16 v[108:111], v[152:155], v[186:189], 0
	v_mfma_f32_16x16x32_bf16 v[92:95], v[140:143], v[198:201], 0
	v_mfma_f32_16x16x32_bf16 v[88:91], v[152:155], v[198:201], 0
	v_mfma_f32_16x16x32_bf16 v[84:87], v[140:143], v[206:209], 0
	v_mfma_f32_16x16x32_bf16 v[76:79], v[152:155], v[206:209], 0
	v_mfma_f32_16x16x32_bf16 v[124:127], v[148:151], v[182:185], v[124:127]
	v_mfma_f32_16x16x32_bf16 v[120:123], v[156:159], v[182:185], v[120:123]
	v_mfma_f32_16x16x32_bf16 v[116:119], v[148:151], v[194:197], v[116:119]
	v_mfma_f32_16x16x32_bf16 v[108:111], v[156:159], v[194:197], v[108:111]
	v_mfma_f32_16x16x32_bf16 v[92:95], v[148:151], v[202:205], v[92:95]
	v_mfma_f32_16x16x32_bf16 v[88:91], v[156:159], v[202:205], v[88:91]
	v_mfma_f32_16x16x32_bf16 v[84:87], v[148:151], v[210:213], v[84:87]
	v_mfma_f32_16x16x32_bf16 v[76:79], v[156:159], v[210:213], v[76:79]
	s_setprio 0
	s_setprio 1
	v_mfma_f32_16x16x32_bf16 v[112:115], v[160:163], v[178:181], 0
	v_mfma_f32_16x16x32_bf16 v[104:107], v[168:171], v[178:181], 0
	v_mfma_f32_16x16x32_bf16 v[100:103], v[160:163], v[186:189], 0
	v_mfma_f32_16x16x32_bf16 v[96:99], v[168:171], v[186:189], 0
	v_mfma_f32_16x16x32_bf16 v[80:83], v[160:163], v[198:201], 0
	v_mfma_f32_16x16x32_bf16 v[72:75], v[168:171], v[198:201], 0
	v_mfma_f32_16x16x32_bf16 v[68:71], v[160:163], v[206:209], 0
	v_mfma_f32_16x16x32_bf16 v[64:67], v[168:171], v[206:209], 0
	v_mfma_f32_16x16x32_bf16 v[112:115], v[164:167], v[182:185], v[112:115]
	v_mfma_f32_16x16x32_bf16 v[104:107], v[172:175], v[182:185], v[104:107]
	v_mfma_f32_16x16x32_bf16 v[100:103], v[164:167], v[194:197], v[100:103]
	v_mfma_f32_16x16x32_bf16 v[96:99], v[172:175], v[194:197], v[96:99]
	v_mfma_f32_16x16x32_bf16 v[80:83], v[164:167], v[202:205], v[80:83]
	v_mfma_f32_16x16x32_bf16 v[72:75], v[172:175], v[202:205], v[72:75]
	v_mfma_f32_16x16x32_bf16 v[68:71], v[164:167], v[210:213], v[68:71]
	v_mfma_f32_16x16x32_bf16 v[64:67], v[172:175], v[210:213], v[64:67]
	s_setprio 0
	s_barrier
	s_add_i32 s37, vcc_lo, s39
	v_lshl_add_u64 v[190:191], s[74:75], 0, v[192:193]
	s_mov_b32 m0, s37
	ds_read_b128 v[178:181], v147 offset:16384
	ds_read_b128 v[182:185], v147 offset:17408
	ds_read_b128 v[186:189], v147 offset:18432
	ds_read_b128 v[194:197], v147 offset:19456
	ds_read_b128 v[198:201], v147 offset:20480
	ds_read_b128 v[202:205], v147 offset:21504
	ds_read_b128 v[206:209], v147 offset:22528
	ds_read_b128 v[210:213], v147 offset:23552
	global_load_lds_dwordx4 v[190:191], off
	s_add_i32 m0, s37, 0x2000
	s_add_u32 vcc_lo, s74, 0x40000
	v_lshl_add_u64 v[214:215], s[74:75], 0, v[132:133]
	s_addc_u32 vcc_hi, s75, 0
	s_add_i32 s35, s35, s39
	global_load_lds_dwordx4 v[214:215], off
	v_lshl_add_u64 v[216:217], vcc, 0, v[192:193]
	s_mov_b32 m0, s35
	v_lshl_add_u64 v[218:219], s[76:77], 0, v[130:131]
	global_load_lds_dwordx4 v[216:217], off
	v_lshl_add_u64 v[216:217], vcc, 0, v[132:133]
	s_add_i32 m0, s35, 0x2000
	s_nop 0
	global_load_lds_dwordx4 v[216:217], off
	v_lshl_add_u64 v[216:217], s[76:77], 0, v[128:129]
	s_mov_b32 m0, s13
	s_nop 0
	global_load_lds_dwordx4 v[216:217], off
	s_mov_b32 m0, s40
	s_nop 0
	global_load_lds_dwordx4 v[218:219], off
	s_waitcnt vmcnt(8)
	s_waitcnt lgkmcnt(0)
	s_barrier
; #define PG8_STAGE(bufoff, gbase, voff) do { _Pragma("unroll") for (int _i = 0; _i < 2; ++_i) \
;         __builtin_amdgcn_global_load_lds((const unsigned*)((const char*)(gbase) + (voff)[_i]), (LAS unsigned*)(lds + (bufoff) + ldsw + _i * 8192), 16, 0, 0); } while (0)
; #define PG8_LDA(dst, b, h) do { _Pragma("unroll") for (int m = 0; m < 4; ++m) _Pragma("unroll") for (int k = 0; k < 2; ++k) dst[m][k] = *(const LAS bf16x8*)(lds + PG8_SA(b, h) + aoff + m * 2048 + k * 1024); } while (0)
; #define PG8_LDB(dst, b, h) do { _Pragma("unroll") for (int n = 0; n < 2; ++n) _Pragma("unroll") for (int k = 0; k < 2; ++k) dst[n][k] = *(const LAS bf16x8*)(lds + PG8_SB(b, h) + boff + n * 2048 + k * 1024); } while (0)
; #define PG8_MMA(ai, bj, At, Bt) do { __builtin_amdgcn_s_setprio(1); _Pragma("unroll") for (int m = 0; m < 4; ++m) _Pragma("unroll") for (int n = 0; n < 2; ++n) _Pragma("unroll") for (int k = 0; k < 2; ++k) \
;         acc[ai][bj][m][n] = __builtin_amdgcn_mfma_f32_16x16x32_bf16(Bt[n][k], At[m][k], acc[ai][bj][m][n], 0, 0, 0); __builtin_amdgcn_s_setprio(0); } while (0)
; #define PG8_WAIT_V(n) asm volatile("s_waitcnt vmcnt(" #n ")" ::: "memory")
; #define PG8_WAIT_L(n) asm volatile("s_waitcnt lgkmcnt(" #n ")" ::: "memory")
; #define PG8_BAR __builtin_amdgcn_s_barrier()
; #define PG8_SCHED __builtin_amdgcn_sched_barrier(0)
; template <class Epi>
; __device__ __forceinline__ void gemm_phase(LAS unsigned char* lds, const Gemm g, const Sched& S, const Epi& E, const int tid) {
;     ...
;             PG8_WAIT_V(8); PG8_WAIT_L(0); PG8_BAR; PG8_MMA(1, 0, At, B0); PG8_MMA(1, 1, At, B1); PG8_BAR; PG8_SCHED;
;             PG8_LDB(B0, 1, 0); PG8_LDB(B1, 1, 1); PG8_SCHED; PG8_LDA(At, 1, 0); PG8_STAGE(PG8_SA(0, 1), a2 + hA, voffA);
;             PG8_WAIT_V(8); PG8_WAIT_L(0); PG8_BAR; PG8_MMA(0, 0, At, B0); PG8_MMA(0, 1, At, B1); PG8_BAR; PG8_SCHED;
	s_setprio 1
	s_waitcnt lgkmcnt(0)
	v_mfma_f32_16x16x32_bf16 v[60:63], v[140:143], v[178:181], 0
	v_mfma_f32_16x16x32_bf16 v[56:59], v[152:155], v[178:181], 0
	v_mfma_f32_16x16x32_bf16 v[52:55], v[140:143], v[186:189], 0
	v_mfma_f32_16x16x32_bf16 v[44:47], v[152:155], v[186:189], 0
	v_mfma_f32_16x16x32_bf16 v[28:31], v[140:143], v[198:201], 0
	v_mfma_f32_16x16x32_bf16 v[24:27], v[152:155], v[198:201], 0
	v_mfma_f32_16x16x32_bf16 v[20:23], v[140:143], v[206:209], 0
	v_mfma_f32_16x16x32_bf16 v[12:15], v[152:155], v[206:209], 0
	v_mfma_f32_16x16x32_bf16 v[60:63], v[148:151], v[182:185], v[60:63]
	v_mfma_f32_16x16x32_bf16 v[56:59], v[156:159], v[182:185], v[56:59]
	v_mfma_f32_16x16x32_bf16 v[52:55], v[148:151], v[194:197], v[52:55]
	v_mfma_f32_16x16x32_bf16 v[44:47], v[156:159], v[194:197], v[44:47]
	v_mfma_f32_16x16x32_bf16 v[28:31], v[148:151], v[202:205], v[28:31]
	v_mfma_f32_16x16x32_bf16 v[24:27], v[156:159], v[202:205], v[24:27]
	v_mfma_f32_16x16x32_bf16 v[20:23], v[148:151], v[210:213], v[20:23]
	v_mfma_f32_16x16x32_bf16 v[12:15], v[156:159], v[210:213], v[12:15]
	s_setprio 0
	s_setprio 1
	v_mfma_f32_16x16x32_bf16 v[48:51], v[160:163], v[178:181], 0
	v_mfma_f32_16x16x32_bf16 v[40:43], v[168:171], v[178:181], 0
	v_mfma_f32_16x16x32_bf16 v[36:39], v[160:163], v[186:189], 0
	v_mfma_f32_16x16x32_bf16 v[32:35], v[168:171], v[186:189], 0
	v_mfma_f32_16x16x32_bf16 v[16:19], v[160:163], v[198:201], 0
	v_mfma_f32_16x16x32_bf16 v[8:11], v[168:171], v[198:201], 0
	v_mfma_f32_16x16x32_bf16 v[4:7], v[160:163], v[206:209], 0
	v_mfma_f32_16x16x32_bf16 v[0:3], v[168:171], v[206:209], 0
	v_mfma_f32_16x16x32_bf16 v[48:51], v[164:167], v[182:185], v[48:51]
	v_mfma_f32_16x16x32_bf16 v[40:43], v[172:175], v[182:185], v[40:43]
	v_mfma_f32_16x16x32_bf16 v[36:39], v[164:167], v[194:197], v[36:39]
	v_mfma_f32_16x16x32_bf16 v[32:35], v[172:175], v[194:197], v[32:35]
	v_mfma_f32_16x16x32_bf16 v[16:19], v[164:167], v[202:205], v[16:19]
	v_mfma_f32_16x16x32_bf16 v[8:11], v[172:175], v[202:205], v[8:11]
	v_mfma_f32_16x16x32_bf16 v[4:7], v[164:167], v[210:213], v[4:7]
	v_mfma_f32_16x16x32_bf16 v[0:3], v[172:175], v[210:213], v[0:3]
	s_setprio 0
	s_barrier
	s_add_i32 s35, 0, 0x18000
	s_add_i32 s37, 0, 0x1c000
	v_add_u32_e32 v156, s35, v145
	v_add_u32_e32 v172, s37, v145
	ds_read_b128 v[140:143], v156
	ds_read_b128 v[148:151], v156 offset:1024
	ds_read_b128 v[152:155], v156 offset:2048
	ds_read_b128 v[156:159], v156 offset:3072
	ds_read_b128 v[160:163], v172
	ds_read_b128 v[164:167], v172 offset:1024
	ds_read_b128 v[168:171], v172 offset:2048
	ds_read_b128 v[172:175], v172 offset:3072
	s_add_u32 s76, s76, 0x40000
	s_addc_u32 s77, s77, 0
	s_mov_b32 m0, s45
	v_lshl_add_u64 v[224:225], s[76:77], 0, v[128:129]
	ds_read_b128 v[178:181], v147 offset:32768
	ds_read_b128 v[182:185], v147 offset:33792
	ds_read_b128 v[186:189], v147 offset:34816
	ds_read_b128 v[194:197], v147 offset:35840
	ds_read_b128 v[198:201], v147 offset:36864
	ds_read_b128 v[202:205], v147 offset:37888
	ds_read_b128 v[206:209], v147 offset:38912
	ds_read_b128 v[210:213], v147 offset:39936
	global_load_lds_dwordx4 v[224:225], off
	v_lshl_add_u64 v[224:225], s[76:77], 0, v[130:131]
	s_mov_b32 m0, s47
	s_nop 0
	global_load_lds_dwordx4 v[224:225], off
	s_waitcnt vmcnt(8)
	s_waitcnt lgkmcnt(0)
	s_barrier
	s_setprio 1
	s_waitcnt lgkmcnt(0)
	v_mfma_f32_16x16x32_bf16 v[124:127], v[140:143], v[178:181], v[124:127]
	v_mfma_f32_16x16x32_bf16 v[120:123], v[152:155], v[178:181], v[120:123]
	v_mfma_f32_16x16x32_bf16 v[116:119], v[140:143], v[186:189], v[116:119]
	v_mfma_f32_16x16x32_bf16 v[108:111], v[152:155], v[186:189], v[108:111]
	v_mfma_f32_16x16x32_bf16 v[92:95], v[140:143], v[198:201], v[92:95]
	v_mfma_f32_16x16x32_bf16 v[88:91], v[152:155], v[198:201], v[88:91]
	v_mfma_f32_16x16x32_bf16 v[84:87], v[140:143], v[206:209], v[84:87]
	v_mfma_f32_16x16x32_bf16 v[76:79], v[152:155], v[206:209], v[76:79]
	v_mfma_f32_16x16x32_bf16 v[124:127], v[148:151], v[182:185], v[124:127]
	v_mfma_f32_16x16x32_bf16 v[120:123], v[156:159], v[182:185], v[120:123]
	v_mfma_f32_16x16x32_bf16 v[116:119], v[148:151], v[194:197], v[116:119]
	v_mfma_f32_16x16x32_bf16 v[108:111], v[156:159], v[194:197], v[108:111]
	v_mfma_f32_16x16x32_bf16 v[92:95], v[148:151], v[202:205], v[92:95]
	v_mfma_f32_16x16x32_bf16 v[88:91], v[156:159], v[202:205], v[88:91]
	v_mfma_f32_16x16x32_bf16 v[84:87], v[148:151], v[210:213], v[84:87]
	v_mfma_f32_16x16x32_bf16 v[76:79], v[156:159], v[210:213], v[76:79]
	s_setprio 0
	s_setprio 1
	v_mfma_f32_16x16x32_bf16 v[112:115], v[160:163], v[178:181], v[112:115]
	v_mfma_f32_16x16x32_bf16 v[104:107], v[168:171], v[178:181], v[104:107]
	v_mfma_f32_16x16x32_bf16 v[100:103], v[160:163], v[186:189], v[100:103]
	v_mfma_f32_16x16x32_bf16 v[96:99], v[168:171], v[186:189], v[96:99]
	v_mfma_f32_16x16x32_bf16 v[80:83], v[160:163], v[198:201], v[80:83]
	v_mfma_f32_16x16x32_bf16 v[72:75], v[168:171], v[198:201], v[72:75]
	v_mfma_f32_16x16x32_bf16 v[68:71], v[160:163], v[206:209], v[68:71]
	v_mfma_f32_16x16x32_bf16 v[64:67], v[168:171], v[206:209], v[64:67]
	v_mfma_f32_16x16x32_bf16 v[112:115], v[164:167], v[182:185], v[112:115]
	v_mfma_f32_16x16x32_bf16 v[104:107], v[172:175], v[182:185], v[104:107]
	v_mfma_f32_16x16x32_bf16 v[100:103], v[164:167], v[194:197], v[100:103]
	v_mfma_f32_16x16x32_bf16 v[96:99], v[172:175], v[194:197], v[96:99]
	v_mfma_f32_16x16x32_bf16 v[80:83], v[164:167], v[202:205], v[80:83]
	v_mfma_f32_16x16x32_bf16 v[72:75], v[172:175], v[202:205], v[72:75]
	v_mfma_f32_16x16x32_bf16 v[68:71], v[164:167], v[210:213], v[68:71]
	v_mfma_f32_16x16x32_bf16 v[64:67], v[172:175], v[210:213], v[64:67]
	s_setprio 0
	s_barrier
; #define PG8_STAGE(bufoff, gbase, voff) do { _Pragma("unroll") for (int _i = 0; _i < 2; ++_i) \
;         __builtin_amdgcn_global_load_lds((const unsigned*)((const char*)(gbase) + (voff)[_i]), (LAS unsigned*)(lds + (bufoff) + ldsw + _i * 8192), 16, 0, 0); } while (0)
; #define PG8_LDA(dst, b, h) do { _Pragma("unroll") for (int m = 0; m < 4; ++m) _Pragma("unroll") for (int k = 0; k < 2; ++k) dst[m][k] = *(const LAS bf16x8*)(lds + PG8_SA(b, h) + aoff + m * 2048 + k * 1024); } while (0)
; #define PG8_MMA(ai, bj, At, Bt) do { __builtin_amdgcn_s_setprio(1); _Pragma("unroll") for (int m = 0; m < 4; ++m) _Pragma("unroll") for (int n = 0; n < 2; ++n) _Pragma("unroll") for (int k = 0; k < 2; ++k) \
;         acc[ai][bj][m][n] = __builtin_amdgcn_mfma_f32_16x16x32_bf16(Bt[n][k], At[m][k], acc[ai][bj][m][n], 0, 0, 0); __builtin_amdgcn_s_setprio(0); } while (0)
; #define PG8_WAIT_V(n) asm volatile("s_waitcnt vmcnt(" #n ")" ::: "memory")
; #define PG8_WAIT_L(n) asm volatile("s_waitcnt lgkmcnt(" #n ")" ::: "memory")
; #define PG8_BAR __builtin_amdgcn_s_barrier()
; #define PG8_SCHED __builtin_amdgcn_sched_barrier(0)
; template <class Epi>
; __device__ __forceinline__ void gemm_phase(LAS unsigned char* lds, const Gemm g, const Sched& S, const Epi& E, const int tid) {
;     ...
;             PG8_LDA(At, 1, 1); PG8_STAGE(PG8_SB(1, 0), b3, voffB); PG8_STAGE(PG8_SB(1, 1), b3 + hB, voffB); PG8_STAGE(PG8_SA(1, 0), a3, voffA);
;             PG8_WAIT_V(8); PG8_WAIT_L(0); PG8_BAR; PG8_MMA(1, 0, At, B0); PG8_MMA(1, 1, At, B1); PG8_BAR; PG8_SCHED;
;         }
	s_add_i32 s35, s35, s39
	v_lshl_add_u64 v[190:191], v[190:191], 0, s[94:95]
	s_mov_b32 m0, s35
	ds_read_b128 v[178:181], v147 offset:49152
	ds_read_b128 v[182:185], v147 offset:50176
	ds_read_b128 v[186:189], v147 offset:51200
	ds_read_b128 v[194:197], v147 offset:52224
	ds_read_b128 v[198:201], v147 offset:53248
	ds_read_b128 v[202:205], v147 offset:54272
	ds_read_b128 v[206:209], v147 offset:55296
	ds_read_b128 v[210:213], v147 offset:56320
	global_load_lds_dwordx4 v[190:191], off
	s_add_i32 m0, s35, 0x2000
	s_add_u32 s74, s74, 0x40080
	v_lshl_add_u64 v[190:191], v[214:215], 0, s[94:95]
	s_addc_u32 s75, s75, 0
	s_add_i32 s35, s37, s39
	global_load_lds_dwordx4 v[190:191], off
	v_lshl_add_u64 v[190:191], s[74:75], 0, v[192:193]
	s_mov_b32 m0, s35
	s_nop 0
	global_load_lds_dwordx4 v[190:191], off
	v_lshl_add_u64 v[190:191], s[74:75], 0, v[132:133]
	s_add_i32 m0, s35, 0x2000
	s_nop 0
	global_load_lds_dwordx4 v[190:191], off
	v_lshl_add_u64 v[190:191], v[216:217], 0, s[94:95]
	s_mov_b32 m0, s78
	s_nop 0
	global_load_lds_dwordx4 v[190:191], off
	v_lshl_add_u64 v[190:191], v[218:219], 0, s[94:95]
	s_mov_b32 m0, s80
	s_nop 0
	global_load_lds_dwordx4 v[190:191], off
	s_waitcnt vmcnt(8)
	s_waitcnt lgkmcnt(0)
	s_barrier
	s_setprio 1
	s_waitcnt lgkmcnt(0)
	v_mfma_f32_16x16x32_bf16 v[60:63], v[140:143], v[178:181], v[60:63]
	v_mfma_f32_16x16x32_bf16 v[56:59], v[152:155], v[178:181], v[56:59]
	v_mfma_f32_16x16x32_bf16 v[52:55], v[140:143], v[186:189], v[52:55]
	v_mfma_f32_16x16x32_bf16 v[44:47], v[152:155], v[186:189], v[44:47]
	v_mfma_f32_16x16x32_bf16 v[28:31], v[140:143], v[198:201], v[28:31]
	v_mfma_f32_16x16x32_bf16 v[24:27], v[152:155], v[198:201], v[24:27]
	v_mfma_f32_16x16x32_bf16 v[20:23], v[140:143], v[206:209], v[20:23]
	v_mfma_f32_16x16x32_bf16 v[12:15], v[152:155], v[206:209], v[12:15]
	v_mfma_f32_16x16x32_bf16 v[60:63], v[148:151], v[182:185], v[60:63]
	v_mfma_f32_16x16x32_bf16 v[56:59], v[156:159], v[182:185], v[56:59]
	v_mfma_f32_16x16x32_bf16 v[52:55], v[148:151], v[194:197], v[52:55]
	v_mfma_f32_16x16x32_bf16 v[44:47], v[156:159], v[194:197], v[44:47]
	v_mfma_f32_16x16x32_bf16 v[28:31], v[148:151], v[202:205], v[28:31]
	v_mfma_f32_16x16x32_bf16 v[24:27], v[156:159], v[202:205], v[24:27]
	v_mfma_f32_16x16x32_bf16 v[20:23], v[148:151], v[210:213], v[20:23]
	v_mfma_f32_16x16x32_bf16 v[12:15], v[156:159], v[210:213], v[12:15]
	s_setprio 0
	s_setprio 1
	v_mfma_f32_16x16x32_bf16 v[48:51], v[160:163], v[178:181], v[48:51]
	v_mfma_f32_16x16x32_bf16 v[40:43], v[168:171], v[178:181], v[40:43]
	v_mfma_f32_16x16x32_bf16 v[36:39], v[160:163], v[186:189], v[36:39]
	v_mfma_f32_16x16x32_bf16 v[32:35], v[168:171], v[186:189], v[32:35]
	v_mfma_f32_16x16x32_bf16 v[16:19], v[160:163], v[198:201], v[16:19]
	v_mfma_f32_16x16x32_bf16 v[8:11], v[168:171], v[198:201], v[8:11]
	v_mfma_f32_16x16x32_bf16 v[4:7], v[160:163], v[206:209], v[4:7]
	v_mfma_f32_16x16x32_bf16 v[0:3], v[168:171], v[206:209], v[0:3]
	v_mfma_f32_16x16x32_bf16 v[48:51], v[164:167], v[182:185], v[48:51]
	v_mfma_f32_16x16x32_bf16 v[40:43], v[172:175], v[182:185], v[40:43]
	v_mfma_f32_16x16x32_bf16 v[36:39], v[164:167], v[194:197], v[36:39]
	v_mfma_f32_16x16x32_bf16 v[32:35], v[172:175], v[194:197], v[32:35]
	v_mfma_f32_16x16x32_bf16 v[16:19], v[164:167], v[202:205], v[16:19]
	v_mfma_f32_16x16x32_bf16 v[8:11], v[172:175], v[202:205], v[8:11]
	v_mfma_f32_16x16x32_bf16 v[4:7], v[164:167], v[210:213], v[4:7]
	v_mfma_f32_16x16x32_bf16 v[0:3], v[172:175], v[210:213], v[0:3]
	s_setprio 0
	s_barrier
	s_add_i32 s21, s21, 2
	s_add_u32 s10, s10, 0x100
	s_addc_u32 s11, s11, 0
	s_add_u32 s9, s9, 0x100
	s_addc_u32 s19, s19, 0
	s_cmp_gt_u32 s21, 13
	s_cbranch_scc1 .Lgk_exit_0

; #define PG8_BAR __builtin_amdgcn_s_barrier()
; template <class Epi>
; __device__ __forceinline__ void gemm_phase(LAS unsigned char* lds, const Gemm g, const Sched& S, const Epi& E, const int tid) {
;     ...
;         if (wr == 0) PG8_BAR;
.Lgk_exit_0:
	s_and_b64 vcc, exec, s[16:17]
	s_cbranch_vccz .LBB0_336
	s_barrier

; #define PG8_STAGE(bufoff, gbase, voff) do { _Pragma("unroll") for (int _i = 0; _i < 2; ++_i) \
;         __builtin_amdgcn_global_load_lds((const unsigned*)((const char*)(gbase) + (voff)[_i]), (LAS unsigned*)(lds + (bufoff) + ldsw + _i * 8192), 16, 0, 0); } while (0)
; #define PG8_LDA(dst, b, h) do { _Pragma("unroll") for (int m = 0; m < 4; ++m) _Pragma("unroll") for (int k = 0; k < 2; ++k) dst[m][k] = *(const LAS bf16x8*)(lds + PG8_SA(b, h) + aoff + m * 2048 + k * 1024); } while (0)
; #define PG8_LDB(dst, b, h) do { _Pragma("unroll") for (int n = 0; n < 2; ++n) _Pragma("unroll") for (int k = 0; k < 2; ++k) dst[n][k] = *(const LAS bf16x8*)(lds + PG8_SB(b, h) + boff + n * 2048 + k * 1024); } while (0)
; #define PG8_MMA(ai, bj, At, Bt) do { __builtin_amdgcn_s_setprio(1); _Pragma("unroll") for (int m = 0; m < 4; ++m) _Pragma("unroll") for (int n = 0; n < 2; ++n) _Pragma("unroll") for (int k = 0; k < 2; ++k) \
;         acc[ai][bj][m][n] = __builtin_amdgcn_mfma_f32_16x16x32_bf16(Bt[n][k], At[m][k], acc[ai][bj][m][n], 0, 0, 0); __builtin_amdgcn_s_setprio(0); } while (0)
; #define PG8_WAIT_V(n) asm volatile("s_waitcnt vmcnt(" #n ")" ::: "memory")
; #define PG8_WAIT_L(n) asm volatile("s_waitcnt lgkmcnt(" #n ")" ::: "memory")
; #define PG8_BAR __builtin_amdgcn_s_barrier()
; #define PG8_SCHED __builtin_amdgcn_sched_barrier(0)
; template <class Epi>
; __device__ __forceinline__ void gemm_phase(LAS unsigned char* lds, const Gemm g, const Sched& S, const Epi& E, const int tid) {
;     ...
;         for (int t = 0; t < nt; t += 2) {
;             const bool last = (t == nt - 2);
;             const char* a1 = cA + (size_t)(t + 1) * kstep;
;             const char* a2 = last ? nA : cA + (size_t)(t + 2) * kstep; const char* b2 = last ? nB : cB + (size_t)(t + 2) * kstep;
;             const char* a3 = a2 + kstep; const char* b3 = b2 + kstep;
;             PG8_LDB(B0, 0, 0); PG8_LDB(B1, 0, 1); PG8_SCHED; PG8_LDA(At, 0, 0); PG8_STAGE(PG8_SA(1, 1), a1 + hA, voffA);
;             PG8_WAIT_V(8); PG8_WAIT_L(0); PG8_BAR; PG8_MMA(0, 0, At, B0); PG8_MMA(0, 1, At, B1); PG8_BAR; PG8_SCHED;
;             PG8_LDA(At, 0, 1); PG8_STAGE(PG8_SB(0, 0), b2, voffB); PG8_STAGE(PG8_SB(0, 1), b2 + hB, voffB); PG8_STAGE(PG8_SA(0, 0), a2, voffA);
.LBB0_993:
	s_add_u32 s13, s18, 0x100
	s_addc_u32 s40, s19, 0
	s_mov_b32 s42, -2
	s_add_u32 s18, s16, 0x100
	s_addc_u32 s19, s17, 0
	s_add_i32 s45, 0, 0x10000
	s_cmp_eq_u32 s42, 4
	s_cselect_b32 s23, s7, s19
	s_cselect_b32 s22, s6, s18
	s_cselect_b32 s21, s15, s40
	s_cselect_b32 s20, s14, s13
	s_add_i32 s51, 0, 0x14000
	v_add_u32_e32 v128, s45, v183
	v_add_u32_e32 v156, s51, v183
	ds_read_b128 v[104:107], v128
	ds_read_b128 v[112:115], v128 offset:1024
	ds_read_b128 v[124:127], v128 offset:2048
	ds_read_b128 v[128:131], v128 offset:3072
	ds_read_b128 v[136:139], v156
	ds_read_b128 v[144:147], v156 offset:1024
	ds_read_b128 v[152:155], v156 offset:2048
	ds_read_b128 v[156:159], v156 offset:3072
	v_lshl_add_u64 v[190:191], s[16:17], 0, v[166:167]
	s_add_i32 m0, s73, 0xc000
	ds_read_b128 v[170:173], v185
	ds_read_b128 v[174:177], v185 offset:1024
	ds_read_b128 v[178:181], v185 offset:2048
	ds_read_b128 v[186:189], v185 offset:3072
	ds_read_b128 v[194:197], v185 offset:4096
	ds_read_b128 v[198:201], v185 offset:5120
	ds_read_b128 v[204:207], v185 offset:6144
	ds_read_b128 v[208:211], v185 offset:7168
	global_load_lds_dwordx4 v[190:191], off
	v_lshl_add_u64 v[190:191], s[16:17], 0, v[168:169]
	s_add_i32 m0, s73, 0xe000
	s_nop 0
	global_load_lds_dwordx4 v[190:191], off
	s_waitcnt vmcnt(8)
	s_waitcnt lgkmcnt(0)
	s_barrier
	s_setprio 1
	s_waitcnt lgkmcnt(0)
	v_mfma_f32_16x16x32_bf16 v[148:151], v[104:107], v[170:173], 0
	v_mfma_f32_16x16x32_bf16 v[140:143], v[124:127], v[170:173], 0
	v_mfma_f32_16x16x32_bf16 v[116:119], v[104:107], v[178:181], 0
	v_mfma_f32_16x16x32_bf16 v[108:111], v[124:127], v[178:181], 0
	v_mfma_f32_16x16x32_bf16 v[92:95], v[104:107], v[194:197], 0
	v_mfma_f32_16x16x32_bf16 v[88:91], v[124:127], v[194:197], 0
	v_mfma_f32_16x16x32_bf16 v[76:79], v[104:107], v[204:207], 0
	v_mfma_f32_16x16x32_bf16 v[72:75], v[124:127], v[204:207], 0
	v_mfma_f32_16x16x32_bf16 v[148:151], v[112:115], v[174:177], v[148:151]
	v_mfma_f32_16x16x32_bf16 v[140:143], v[128:131], v[174:177], v[140:143]
	v_mfma_f32_16x16x32_bf16 v[116:119], v[112:115], v[186:189], v[116:119]
	v_mfma_f32_16x16x32_bf16 v[108:111], v[128:131], v[186:189], v[108:111]
	v_mfma_f32_16x16x32_bf16 v[92:95], v[112:115], v[198:201], v[92:95]
	v_mfma_f32_16x16x32_bf16 v[88:91], v[128:131], v[198:201], v[88:91]
	v_mfma_f32_16x16x32_bf16 v[76:79], v[112:115], v[208:211], v[76:79]
	v_mfma_f32_16x16x32_bf16 v[72:75], v[128:131], v[208:211], v[72:75]
	s_setprio 0
	s_setprio 1
	v_mfma_f32_16x16x32_bf16 v[132:135], v[136:139], v[170:173], 0
	v_mfma_f32_16x16x32_bf16 v[120:123], v[152:155], v[170:173], 0
	v_mfma_f32_16x16x32_bf16 v[100:103], v[136:139], v[178:181], 0
	v_mfma_f32_16x16x32_bf16 v[96:99], v[152:155], v[178:181], 0
	v_mfma_f32_16x16x32_bf16 v[84:87], v[136:139], v[194:197], 0
	v_mfma_f32_16x16x32_bf16 v[80:83], v[152:155], v[194:197], 0
	v_mfma_f32_16x16x32_bf16 v[68:71], v[136:139], v[204:207], 0
	v_mfma_f32_16x16x32_bf16 v[64:67], v[152:155], v[204:207], 0
	v_mfma_f32_16x16x32_bf16 v[132:135], v[144:147], v[174:177], v[132:135]
	v_mfma_f32_16x16x32_bf16 v[120:123], v[156:159], v[174:177], v[120:123]
	v_mfma_f32_16x16x32_bf16 v[100:103], v[144:147], v[186:189], v[100:103]
	v_mfma_f32_16x16x32_bf16 v[96:99], v[156:159], v[186:189], v[96:99]
	v_mfma_f32_16x16x32_bf16 v[84:87], v[144:147], v[198:201], v[84:87]
	v_mfma_f32_16x16x32_bf16 v[80:83], v[156:159], v[198:201], v[80:83]
	v_mfma_f32_16x16x32_bf16 v[68:71], v[144:147], v[208:211], v[68:71]
	v_mfma_f32_16x16x32_bf16 v[64:67], v[156:159], v[208:211], v[64:67]
	s_setprio 0
	s_barrier
	s_add_i32 s16, s45, s47
	v_lshl_add_u64 v[190:191], s[20:21], 0, v[192:193]
	s_mov_b32 m0, s16
	ds_read_b128 v[170:173], v185 offset:16384
	ds_read_b128 v[174:177], v185 offset:17408
	ds_read_b128 v[178:181], v185 offset:18432
	ds_read_b128 v[186:189], v185 offset:19456
	ds_read_b128 v[194:197], v185 offset:20480
	ds_read_b128 v[198:201], v185 offset:21504
	ds_read_b128 v[204:207], v185 offset:22528
	ds_read_b128 v[208:211], v185 offset:23552
	global_load_lds_dwordx4 v[190:191], off
	s_add_i32 m0, s16, 0x2000
	s_add_u32 s16, s20, 0x20000
	v_lshl_add_u64 v[212:213], s[20:21], 0, v[164:165]
	s_addc_u32 s17, s21, 0
	s_add_i32 s45, s51, s47
	global_load_lds_dwordx4 v[212:213], off
	v_lshl_add_u64 v[214:215], s[16:17], 0, v[192:193]
	s_mov_b32 m0, s45
	v_lshl_add_u64 v[216:217], s[22:23], 0, v[162:163]
	global_load_lds_dwordx4 v[214:215], off
	v_lshl_add_u64 v[214:215], s[16:17], 0, v[164:165]
	s_add_i32 m0, s45, 0x2000
	s_nop 0
	global_load_lds_dwordx4 v[214:215], off
	v_lshl_add_u64 v[214:215], s[22:23], 0, v[160:161]
	s_mov_b32 m0, s73
	s_nop 0
	global_load_lds_dwordx4 v[214:215], off
	s_mov_b32 m0, s74
	s_nop 0
	global_load_lds_dwordx4 v[216:217], off
	s_waitcnt vmcnt(8)
	s_waitcnt lgkmcnt(0)
	s_barrier
; #define PG8_STAGE(bufoff, gbase, voff) do { _Pragma("unroll") for (int _i = 0; _i < 2; ++_i) \
;         __builtin_amdgcn_global_load_lds((const unsigned*)((const char*)(gbase) + (voff)[_i]), (LAS unsigned*)(lds + (bufoff) + ldsw + _i * 8192), 16, 0, 0); } while (0)
; #define PG8_LDA(dst, b, h) do { _Pragma("unroll") for (int m = 0; m < 4; ++m) _Pragma("unroll") for (int k = 0; k < 2; ++k) dst[m][k] = *(const LAS bf16x8*)(lds + PG8_SA(b, h) + aoff + m * 2048 + k * 1024); } while (0)
; #define PG8_LDB(dst, b, h) do { _Pragma("unroll") for (int n = 0; n < 2; ++n) _Pragma("unroll") for (int k = 0; k < 2; ++k) dst[n][k] = *(const LAS bf16x8*)(lds + PG8_SB(b, h) + boff + n * 2048 + k * 1024); } while (0)
; #define PG8_MMA(ai, bj, At, Bt) do { __builtin_amdgcn_s_setprio(1); _Pragma("unroll") for (int m = 0; m < 4; ++m) _Pragma("unroll") for (int n = 0; n < 2; ++n) _Pragma("unroll") for (int k = 0; k < 2; ++k) \
;         acc[ai][bj][m][n] = __builtin_amdgcn_mfma_f32_16x16x32_bf16(Bt[n][k], At[m][k], acc[ai][bj][m][n], 0, 0, 0); __builtin_amdgcn_s_setprio(0); } while (0)
; #define PG8_WAIT_V(n) asm volatile("s_waitcnt vmcnt(" #n ")" ::: "memory")
; #define PG8_WAIT_L(n) asm volatile("s_waitcnt lgkmcnt(" #n ")" ::: "memory")
; #define PG8_BAR __builtin_amdgcn_s_barrier()
; #define PG8_SCHED __builtin_amdgcn_sched_barrier(0)
; template <class Epi>
; __device__ __forceinline__ void gemm_phase(LAS unsigned char* lds, const Gemm g, const Sched& S, const Epi& E, const int tid) {
;     ...
;             PG8_WAIT_V(8); PG8_WAIT_L(0); PG8_BAR; PG8_MMA(1, 0, At, B0); PG8_MMA(1, 1, At, B1); PG8_BAR; PG8_SCHED;
;             PG8_LDB(B0, 1, 0); PG8_LDB(B1, 1, 1); PG8_SCHED; PG8_LDA(At, 1, 0); PG8_STAGE(PG8_SA(0, 1), a2 + hA, voffA);
;             PG8_WAIT_V(8); PG8_WAIT_L(0); PG8_BAR; PG8_MMA(0, 0, At, B0); PG8_MMA(0, 1, At, B1); PG8_BAR; PG8_SCHED;
	s_setprio 1
	s_waitcnt lgkmcnt(0)
	v_mfma_f32_16x16x32_bf16 v[60:63], v[104:107], v[170:173], 0
	v_mfma_f32_16x16x32_bf16 v[56:59], v[124:127], v[170:173], 0
	v_mfma_f32_16x16x32_bf16 v[44:47], v[104:107], v[178:181], 0
	v_mfma_f32_16x16x32_bf16 v[40:43], v[124:127], v[178:181], 0
	v_mfma_f32_16x16x32_bf16 v[28:31], v[104:107], v[194:197], 0
	v_mfma_f32_16x16x32_bf16 v[24:27], v[124:127], v[194:197], 0
	v_mfma_f32_16x16x32_bf16 v[12:15], v[104:107], v[204:207], 0
	v_mfma_f32_16x16x32_bf16 v[8:11], v[124:127], v[204:207], 0
	v_mfma_f32_16x16x32_bf16 v[60:63], v[112:115], v[174:177], v[60:63]
	v_mfma_f32_16x16x32_bf16 v[56:59], v[128:131], v[174:177], v[56:59]
	v_mfma_f32_16x16x32_bf16 v[44:47], v[112:115], v[186:189], v[44:47]
	v_mfma_f32_16x16x32_bf16 v[40:43], v[128:131], v[186:189], v[40:43]
	v_mfma_f32_16x16x32_bf16 v[28:31], v[112:115], v[198:201], v[28:31]
	v_mfma_f32_16x16x32_bf16 v[24:27], v[128:131], v[198:201], v[24:27]
	v_mfma_f32_16x16x32_bf16 v[12:15], v[112:115], v[208:211], v[12:15]
	v_mfma_f32_16x16x32_bf16 v[8:11], v[128:131], v[208:211], v[8:11]
	s_setprio 0
	s_setprio 1
	v_mfma_f32_16x16x32_bf16 v[52:55], v[136:139], v[170:173], 0
	v_mfma_f32_16x16x32_bf16 v[48:51], v[152:155], v[170:173], 0
	v_mfma_f32_16x16x32_bf16 v[36:39], v[136:139], v[178:181], 0
	v_mfma_f32_16x16x32_bf16 v[32:35], v[152:155], v[178:181], 0
	v_mfma_f32_16x16x32_bf16 v[20:23], v[136:139], v[194:197], 0
	v_mfma_f32_16x16x32_bf16 v[16:19], v[152:155], v[194:197], 0
	v_mfma_f32_16x16x32_bf16 v[4:7], v[136:139], v[204:207], 0
	v_mfma_f32_16x16x32_bf16 v[0:3], v[152:155], v[204:207], 0
	v_mfma_f32_16x16x32_bf16 v[52:55], v[144:147], v[174:177], v[52:55]
	v_mfma_f32_16x16x32_bf16 v[48:51], v[156:159], v[174:177], v[48:51]
	v_mfma_f32_16x16x32_bf16 v[36:39], v[144:147], v[186:189], v[36:39]
	v_mfma_f32_16x16x32_bf16 v[32:35], v[156:159], v[186:189], v[32:35]
	v_mfma_f32_16x16x32_bf16 v[20:23], v[144:147], v[198:201], v[20:23]
	v_mfma_f32_16x16x32_bf16 v[16:19], v[156:159], v[198:201], v[16:19]
	v_mfma_f32_16x16x32_bf16 v[4:7], v[144:147], v[208:211], v[4:7]
	v_mfma_f32_16x16x32_bf16 v[0:3], v[156:159], v[208:211], v[0:3]
	s_setprio 0
	s_barrier
	s_add_i32 s45, 0, 0x18000
	s_add_i32 s51, 0, 0x1c000
	v_add_u32_e32 v128, s45, v183
	v_add_u32_e32 v156, s51, v183
	ds_read_b128 v[104:107], v128
	ds_read_b128 v[112:115], v128 offset:1024
	ds_read_b128 v[124:127], v128 offset:2048
	ds_read_b128 v[128:131], v128 offset:3072
	ds_read_b128 v[136:139], v156
	ds_read_b128 v[144:147], v156 offset:1024
	ds_read_b128 v[152:155], v156 offset:2048
	ds_read_b128 v[156:159], v156 offset:3072
	s_add_u32 s16, s22, 0x120000
	s_addc_u32 s17, s23, 0
	s_mov_b32 m0, s75
	v_lshl_add_u64 v[218:219], s[16:17], 0, v[160:161]
	ds_read_b128 v[170:173], v185 offset:32768
	ds_read_b128 v[174:177], v185 offset:33792
	ds_read_b128 v[178:181], v185 offset:34816
	ds_read_b128 v[186:189], v185 offset:35840
	ds_read_b128 v[194:197], v185 offset:36864
	ds_read_b128 v[198:201], v185 offset:37888
	ds_read_b128 v[204:207], v185 offset:38912
	ds_read_b128 v[208:211], v185 offset:39936
	global_load_lds_dwordx4 v[218:219], off
	v_lshl_add_u64 v[218:219], s[16:17], 0, v[162:163]
	s_mov_b32 m0, s76
	s_nop 0
	global_load_lds_dwordx4 v[218:219], off
	s_waitcnt vmcnt(8)
	s_waitcnt lgkmcnt(0)
	s_barrier
	s_setprio 1
	s_waitcnt lgkmcnt(0)
	v_mfma_f32_16x16x32_bf16 v[148:151], v[104:107], v[170:173], v[148:151]
	v_mfma_f32_16x16x32_bf16 v[140:143], v[124:127], v[170:173], v[140:143]
	v_mfma_f32_16x16x32_bf16 v[116:119], v[104:107], v[178:181], v[116:119]
	v_mfma_f32_16x16x32_bf16 v[108:111], v[124:127], v[178:181], v[108:111]
	v_mfma_f32_16x16x32_bf16 v[92:95], v[104:107], v[194:197], v[92:95]
	v_mfma_f32_16x16x32_bf16 v[88:91], v[124:127], v[194:197], v[88:91]
	v_mfma_f32_16x16x32_bf16 v[76:79], v[104:107], v[204:207], v[76:79]
	v_mfma_f32_16x16x32_bf16 v[72:75], v[124:127], v[204:207], v[72:75]
	v_mfma_f32_16x16x32_bf16 v[148:151], v[112:115], v[174:177], v[148:151]
	v_mfma_f32_16x16x32_bf16 v[140:143], v[128:131], v[174:177], v[140:143]
	v_mfma_f32_16x16x32_bf16 v[116:119], v[112:115], v[186:189], v[116:119]
	v_mfma_f32_16x16x32_bf16 v[108:111], v[128:131], v[186:189], v[108:111]
	v_mfma_f32_16x16x32_bf16 v[92:95], v[112:115], v[198:201], v[92:95]
	v_mfma_f32_16x16x32_bf16 v[88:91], v[128:131], v[198:201], v[88:91]
	v_mfma_f32_16x16x32_bf16 v[76:79], v[112:115], v[208:211], v[76:79]
	v_mfma_f32_16x16x32_bf16 v[72:75], v[128:131], v[208:211], v[72:75]
	s_setprio 0
	s_setprio 1
	v_mfma_f32_16x16x32_bf16 v[132:135], v[136:139], v[170:173], v[132:135]
	v_mfma_f32_16x16x32_bf16 v[120:123], v[152:155], v[170:173], v[120:123]
	v_mfma_f32_16x16x32_bf16 v[100:103], v[136:139], v[178:181], v[100:103]
	v_mfma_f32_16x16x32_bf16 v[96:99], v[152:155], v[178:181], v[96:99]
	v_mfma_f32_16x16x32_bf16 v[84:87], v[136:139], v[194:197], v[84:87]
	v_mfma_f32_16x16x32_bf16 v[80:83], v[152:155], v[194:197], v[80:83]
	v_mfma_f32_16x16x32_bf16 v[68:71], v[136:139], v[204:207], v[68:71]
	v_mfma_f32_16x16x32_bf16 v[64:67], v[152:155], v[204:207], v[64:67]
	v_mfma_f32_16x16x32_bf16 v[132:135], v[144:147], v[174:177], v[132:135]
	v_mfma_f32_16x16x32_bf16 v[120:123], v[156:159], v[174:177], v[120:123]
	v_mfma_f32_16x16x32_bf16 v[100:103], v[144:147], v[186:189], v[100:103]
	v_mfma_f32_16x16x32_bf16 v[96:99], v[156:159], v[186:189], v[96:99]
	v_mfma_f32_16x16x32_bf16 v[84:87], v[144:147], v[198:201], v[84:87]
	v_mfma_f32_16x16x32_bf16 v[80:83], v[156:159], v[198:201], v[80:83]
	v_mfma_f32_16x16x32_bf16 v[68:71], v[144:147], v[208:211], v[68:71]
	v_mfma_f32_16x16x32_bf16 v[64:67], v[156:159], v[208:211], v[64:67]
	s_setprio 0
	s_barrier
; #define PG8_STAGE(bufoff, gbase, voff) do { _Pragma("unroll") for (int _i = 0; _i < 2; ++_i) \
;         __builtin_amdgcn_global_load_lds((const unsigned*)((const char*)(gbase) + (voff)[_i]), (LAS unsigned*)(lds + (bufoff) + ldsw + _i * 8192), 16, 0, 0); } while (0)
; #define PG8_LDA(dst, b, h) do { _Pragma("unroll") for (int m = 0; m < 4; ++m) _Pragma("unroll") for (int k = 0; k < 2; ++k) dst[m][k] = *(const LAS bf16x8*)(lds + PG8_SA(b, h) + aoff + m * 2048 + k * 1024); } while (0)
; #define PG8_MMA(ai, bj, At, Bt) do { __builtin_amdgcn_s_setprio(1); _Pragma("unroll") for (int m = 0; m < 4; ++m) _Pragma("unroll") for (int n = 0; n < 2; ++n) _Pragma("unroll") for (int k = 0; k < 2; ++k) \
;         acc[ai][bj][m][n] = __builtin_amdgcn_mfma_f32_16x16x32_bf16(Bt[n][k], At[m][k], acc[ai][bj][m][n], 0, 0, 0); __builtin_amdgcn_s_setprio(0); } while (0)
; #define PG8_WAIT_V(n) asm volatile("s_waitcnt vmcnt(" #n ")" ::: "memory")
; #define PG8_WAIT_L(n) asm volatile("s_waitcnt lgkmcnt(" #n ")" ::: "memory")
; #define PG8_BAR __builtin_amdgcn_s_barrier()
; #define PG8_SCHED __builtin_amdgcn_sched_barrier(0)
; template <class Epi>
; __device__ __forceinline__ void gemm_phase(LAS unsigned char* lds, const Gemm g, const Sched& S, const Epi& E, const int tid) {
;     ...
;             PG8_LDA(At, 1, 1); PG8_STAGE(PG8_SB(1, 0), b3, voffB); PG8_STAGE(PG8_SB(1, 1), b3 + hB, voffB); PG8_STAGE(PG8_SA(1, 0), a3, voffA);
;             PG8_WAIT_V(8); PG8_WAIT_L(0); PG8_BAR; PG8_MMA(1, 0, At, B0); PG8_MMA(1, 1, At, B1); PG8_BAR; PG8_SCHED;
;         }
	s_add_i32 s16, s45, s47
	v_lshl_add_u64 v[190:191], v[190:191], 0, s[94:95]
	s_mov_b32 m0, s16
	ds_read_b128 v[170:173], v185 offset:49152
	ds_read_b128 v[174:177], v185 offset:50176
	ds_read_b128 v[178:181], v185 offset:51200
	ds_read_b128 v[186:189], v185 offset:52224
	ds_read_b128 v[194:197], v185 offset:53248
	ds_read_b128 v[198:201], v185 offset:54272
	ds_read_b128 v[204:207], v185 offset:55296
	ds_read_b128 v[208:211], v185 offset:56320
	global_load_lds_dwordx4 v[190:191], off
	s_add_i32 m0, s16, 0x2000
	s_add_u32 s16, s20, 0x20080
	v_lshl_add_u64 v[190:191], v[212:213], 0, s[94:95]
	s_addc_u32 s17, s21, 0
	s_add_i32 s20, s51, s47
	global_load_lds_dwordx4 v[190:191], off
	v_lshl_add_u64 v[190:191], s[16:17], 0, v[192:193]
	s_mov_b32 m0, s20
	s_nop 0
	global_load_lds_dwordx4 v[190:191], off
	v_lshl_add_u64 v[190:191], s[16:17], 0, v[164:165]
	s_add_i32 m0, s20, 0x2000
	s_nop 0
	global_load_lds_dwordx4 v[190:191], off
	v_lshl_add_u64 v[190:191], v[214:215], 0, s[94:95]
	s_mov_b32 m0, s77
	s_nop 0
	global_load_lds_dwordx4 v[190:191], off
	v_lshl_add_u64 v[190:191], v[216:217], 0, s[94:95]
	s_mov_b32 m0, s78
	s_nop 0
	global_load_lds_dwordx4 v[190:191], off
	s_waitcnt vmcnt(8)
	s_waitcnt lgkmcnt(0)
	s_barrier
	s_setprio 1
	s_waitcnt lgkmcnt(0)
	v_mfma_f32_16x16x32_bf16 v[60:63], v[104:107], v[170:173], v[60:63]
	v_mfma_f32_16x16x32_bf16 v[56:59], v[124:127], v[170:173], v[56:59]
	v_mfma_f32_16x16x32_bf16 v[44:47], v[104:107], v[178:181], v[44:47]
	v_mfma_f32_16x16x32_bf16 v[40:43], v[124:127], v[178:181], v[40:43]
	v_mfma_f32_16x16x32_bf16 v[28:31], v[104:107], v[194:197], v[28:31]
	v_mfma_f32_16x16x32_bf16 v[24:27], v[124:127], v[194:197], v[24:27]
	v_mfma_f32_16x16x32_bf16 v[12:15], v[104:107], v[204:207], v[12:15]
	v_mfma_f32_16x16x32_bf16 v[8:11], v[124:127], v[204:207], v[8:11]
	v_mfma_f32_16x16x32_bf16 v[60:63], v[112:115], v[174:177], v[60:63]
	v_mfma_f32_16x16x32_bf16 v[56:59], v[128:131], v[174:177], v[56:59]
	v_mfma_f32_16x16x32_bf16 v[44:47], v[112:115], v[186:189], v[44:47]
	v_mfma_f32_16x16x32_bf16 v[40:43], v[128:131], v[186:189], v[40:43]
	v_mfma_f32_16x16x32_bf16 v[28:31], v[112:115], v[198:201], v[28:31]
	v_mfma_f32_16x16x32_bf16 v[24:27], v[128:131], v[198:201], v[24:27]
	v_mfma_f32_16x16x32_bf16 v[12:15], v[112:115], v[208:211], v[12:15]
	v_mfma_f32_16x16x32_bf16 v[8:11], v[128:131], v[208:211], v[8:11]
	s_setprio 0
	s_setprio 1
	v_mfma_f32_16x16x32_bf16 v[52:55], v[136:139], v[170:173], v[52:55]
	v_mfma_f32_16x16x32_bf16 v[48:51], v[152:155], v[170:173], v[48:51]
	v_mfma_f32_16x16x32_bf16 v[36:39], v[136:139], v[178:181], v[36:39]
	v_mfma_f32_16x16x32_bf16 v[32:35], v[152:155], v[178:181], v[32:35]
	v_mfma_f32_16x16x32_bf16 v[20:23], v[136:139], v[194:197], v[20:23]
	v_mfma_f32_16x16x32_bf16 v[16:19], v[152:155], v[194:197], v[16:19]
	v_mfma_f32_16x16x32_bf16 v[4:7], v[136:139], v[204:207], v[4:7]
	v_mfma_f32_16x16x32_bf16 v[0:3], v[152:155], v[204:207], v[0:3]
	v_mfma_f32_16x16x32_bf16 v[52:55], v[144:147], v[174:177], v[52:55]
	v_mfma_f32_16x16x32_bf16 v[48:51], v[156:159], v[174:177], v[48:51]
	v_mfma_f32_16x16x32_bf16 v[36:39], v[144:147], v[186:189], v[36:39]
	v_mfma_f32_16x16x32_bf16 v[32:35], v[156:159], v[186:189], v[32:35]
	v_mfma_f32_16x16x32_bf16 v[20:23], v[144:147], v[198:201], v[20:23]
	v_mfma_f32_16x16x32_bf16 v[16:19], v[156:159], v[198:201], v[16:19]
	v_mfma_f32_16x16x32_bf16 v[4:7], v[144:147], v[208:211], v[4:7]
	v_mfma_f32_16x16x32_bf16 v[0:3], v[156:159], v[208:211], v[0:3]
	s_setprio 0
	s_barrier
	s_add_i32 s42, s42, 2
	s_add_u32 s13, s13, 0x100
	s_addc_u32 s40, s40, 0
	s_cmp_gt_u32 s42, 5
	s_mov_b64 s[16:17], s[18:19]
	s_cbranch_scc1 .Lgk_exit_1

; #define PG8_BAR __builtin_amdgcn_s_barrier()
; template <class Epi>
; __device__ __forceinline__ void gemm_phase(LAS unsigned char* lds, const Gemm g, const Sched& S, const Epi& E, const int tid) {
;     ...
;         if (wr == 0) PG8_BAR;
.Lgk_exit_1:
	s_and_b64 vcc, exec, s[10:11]
	s_cbranch_vccz .LBB0_997
	s_barrier

; #define PG8_STAGE(bufoff, gbase, voff) do { _Pragma("unroll") for (int _i = 0; _i < 2; ++_i) \
;         __builtin_amdgcn_global_load_lds((const unsigned*)((const char*)(gbase) + (voff)[_i]), (LAS unsigned*)(lds + (bufoff) + ldsw + _i * 8192), 16, 0, 0); } while (0)
; #define PG8_LDA(dst, b, h) do { _Pragma("unroll") for (int m = 0; m < 4; ++m) _Pragma("unroll") for (int k = 0; k < 2; ++k) dst[m][k] = *(const LAS bf16x8*)(lds + PG8_SA(b, h) + aoff + m * 2048 + k * 1024); } while (0)
; #define PG8_LDB(dst, b, h) do { _Pragma("unroll") for (int n = 0; n < 2; ++n) _Pragma("unroll") for (int k = 0; k < 2; ++k) dst[n][k] = *(const LAS bf16x8*)(lds + PG8_SB(b, h) + boff + n * 2048 + k * 1024); } while (0)
; #define PG8_MMA(ai, bj, At, Bt) do { __builtin_amdgcn_s_setprio(1); _Pragma("unroll") for (int m = 0; m < 4; ++m) _Pragma("unroll") for (int n = 0; n < 2; ++n) _Pragma("unroll") for (int k = 0; k < 2; ++k) \
;         acc[ai][bj][m][n] = __builtin_amdgcn_mfma_f32_16x16x32_bf16(Bt[n][k], At[m][k], acc[ai][bj][m][n], 0, 0, 0); __builtin_amdgcn_s_setprio(0); } while (0)
; #define PG8_WAIT_V(n) asm volatile("s_waitcnt vmcnt(" #n ")" ::: "memory")
; #define PG8_WAIT_L(n) asm volatile("s_waitcnt lgkmcnt(" #n ")" ::: "memory")
; #define PG8_BAR __builtin_amdgcn_s_barrier()
; #define PG8_SCHED __builtin_amdgcn_sched_barrier(0)
; template <class Epi>
; __device__ __forceinline__ void gemm_phase(LAS unsigned char* lds, const Gemm g, const Sched& S, const Epi& E, const int tid) {
;     ...
;         for (int t = 0; t < nt; t += 2) {
;             const bool last = (t == nt - 2);
;             const char* a1 = cA + (size_t)(t + 1) * kstep;
;             const char* a2 = last ? nA : cA + (size_t)(t + 2) * kstep; const char* b2 = last ? nB : cB + (size_t)(t + 2) * kstep;
;             const char* a3 = a2 + kstep; const char* b3 = b2 + kstep;
;             PG8_LDB(B0, 0, 0); PG8_LDB(B1, 0, 1); PG8_SCHED; PG8_LDA(At, 0, 0); PG8_STAGE(PG8_SA(1, 1), a1 + hA, voffA);
;             PG8_WAIT_V(8); PG8_WAIT_L(0); PG8_BAR; PG8_MMA(0, 0, At, B0); PG8_MMA(0, 1, At, B1); PG8_BAR; PG8_SCHED;
;             PG8_LDA(At, 0, 1); PG8_STAGE(PG8_SB(0, 0), b2, voffB); PG8_STAGE(PG8_SB(0, 1), b2 + hB, voffB); PG8_STAGE(PG8_SA(0, 0), a2, voffA);
.LBB0_1028:
	s_add_u32 s13, s22, 0x100
	s_addc_u32 s37, s23, 0
	s_mov_b32 s40, -2
	s_add_u32 s6, s20, 0x100
	s_addc_u32 s7, s21, 0
	s_add_i32 s42, 0, 0x10000
	s_cmp_eq_u32 s40, 4
	s_cselect_b32 s73, s15, s7
	s_cselect_b32 s72, s14, s6
	s_cselect_b32 s23, s17, s37
	s_cselect_b32 s22, s16, s13
	s_add_i32 s45, 0, 0x14000
	v_add_u32_e32 v128, s42, v241
	v_add_u32_e32 v156, s45, v241
	ds_read_b128 v[104:107], v128
	ds_read_b128 v[112:115], v128 offset:1024
	ds_read_b128 v[120:123], v128 offset:2048
	ds_read_b128 v[128:131], v128 offset:3072
	ds_read_b128 v[136:139], v156
	ds_read_b128 v[140:143], v156 offset:1024
	ds_read_b128 v[148:151], v156 offset:2048
	ds_read_b128 v[156:159], v156 offset:3072
	v_lshl_add_u64 v[194:195], s[20:21], 0, v[210:211]
	s_add_i32 m0, s19, 0xc000
	ds_read_b128 v[160:163], v243
	ds_read_b128 v[164:167], v243 offset:1024
	ds_read_b128 v[168:171], v243 offset:2048
	ds_read_b128 v[172:175], v243 offset:3072
	ds_read_b128 v[176:179], v243 offset:4096
	ds_read_b128 v[180:183], v243 offset:5120
	ds_read_b128 v[184:187], v243 offset:6144
	ds_read_b128 v[188:191], v243 offset:7168
	global_load_lds_dwordx4 v[194:195], off
	v_lshl_add_u64 v[194:195], s[20:21], 0, v[212:213]
	s_add_i32 m0, s19, 0xe000
	s_nop 0
	global_load_lds_dwordx4 v[194:195], off
	s_waitcnt vmcnt(8)
	s_waitcnt lgkmcnt(0)
	s_barrier
	s_setprio 1
	s_waitcnt lgkmcnt(0)
	v_mfma_f32_16x16x32_bf16 v[152:155], v[104:107], v[160:163], 0
	v_mfma_f32_16x16x32_bf16 v[144:147], v[120:123], v[160:163], 0
	v_mfma_f32_16x16x32_bf16 v[116:119], v[104:107], v[168:171], 0
	v_mfma_f32_16x16x32_bf16 v[108:111], v[120:123], v[168:171], 0
	v_mfma_f32_16x16x32_bf16 v[92:95], v[104:107], v[176:179], 0
	v_mfma_f32_16x16x32_bf16 v[88:91], v[120:123], v[176:179], 0
	v_mfma_f32_16x16x32_bf16 v[76:79], v[104:107], v[184:187], 0
	v_mfma_f32_16x16x32_bf16 v[72:75], v[120:123], v[184:187], 0
	v_mfma_f32_16x16x32_bf16 v[152:155], v[112:115], v[164:167], v[152:155]
	v_mfma_f32_16x16x32_bf16 v[144:147], v[128:131], v[164:167], v[144:147]
	v_mfma_f32_16x16x32_bf16 v[116:119], v[112:115], v[172:175], v[116:119]
	v_mfma_f32_16x16x32_bf16 v[108:111], v[128:131], v[172:175], v[108:111]
	v_mfma_f32_16x16x32_bf16 v[92:95], v[112:115], v[180:183], v[92:95]
	v_mfma_f32_16x16x32_bf16 v[88:91], v[128:131], v[180:183], v[88:91]
	v_mfma_f32_16x16x32_bf16 v[76:79], v[112:115], v[188:191], v[76:79]
	v_mfma_f32_16x16x32_bf16 v[72:75], v[128:131], v[188:191], v[72:75]
	s_setprio 0
	s_setprio 1
	v_mfma_f32_16x16x32_bf16 v[132:135], v[136:139], v[160:163], 0
	v_mfma_f32_16x16x32_bf16 v[124:127], v[148:151], v[160:163], 0
	v_mfma_f32_16x16x32_bf16 v[100:103], v[136:139], v[168:171], 0
	v_mfma_f32_16x16x32_bf16 v[96:99], v[148:151], v[168:171], 0
	v_mfma_f32_16x16x32_bf16 v[84:87], v[136:139], v[176:179], 0
	v_mfma_f32_16x16x32_bf16 v[80:83], v[148:151], v[176:179], 0
	v_mfma_f32_16x16x32_bf16 v[68:71], v[136:139], v[184:187], 0
	v_mfma_f32_16x16x32_bf16 v[64:67], v[148:151], v[184:187], 0
	v_mfma_f32_16x16x32_bf16 v[132:135], v[140:143], v[164:167], v[132:135]
	v_mfma_f32_16x16x32_bf16 v[124:127], v[156:159], v[164:167], v[124:127]
	v_mfma_f32_16x16x32_bf16 v[100:103], v[140:143], v[172:175], v[100:103]
	v_mfma_f32_16x16x32_bf16 v[96:99], v[156:159], v[172:175], v[96:99]
	v_mfma_f32_16x16x32_bf16 v[84:87], v[140:143], v[180:183], v[84:87]
	v_mfma_f32_16x16x32_bf16 v[80:83], v[156:159], v[180:183], v[80:83]
	v_mfma_f32_16x16x32_bf16 v[68:71], v[140:143], v[188:191], v[68:71]
	v_mfma_f32_16x16x32_bf16 v[64:67], v[156:159], v[188:191], v[64:67]
	s_setprio 0
	s_barrier
	s_add_i32 s20, s42, s35
	v_lshl_add_u64 v[194:195], s[22:23], 0, v[192:193]
	s_mov_b32 m0, s20
	ds_read_b128 v[160:163], v243 offset:16384
	ds_read_b128 v[164:167], v243 offset:17408
	ds_read_b128 v[168:171], v243 offset:18432
	ds_read_b128 v[172:175], v243 offset:19456
	ds_read_b128 v[176:179], v243 offset:20480
	ds_read_b128 v[180:183], v243 offset:21504
	ds_read_b128 v[184:187], v243 offset:22528
	ds_read_b128 v[188:191], v243 offset:23552
	global_load_lds_dwordx4 v[194:195], off
	s_add_i32 m0, s20, 0x2000
	s_add_u32 s20, s22, 0x20000
	v_lshl_add_u64 v[196:197], s[22:23], 0, v[208:209]
	s_addc_u32 s21, s23, 0
	s_add_i32 s42, s45, s35
	global_load_lds_dwordx4 v[196:197], off
	v_lshl_add_u64 v[198:199], s[20:21], 0, v[192:193]
	s_mov_b32 m0, s42
	v_lshl_add_u64 v[200:201], s[72:73], 0, v[206:207]
	global_load_lds_dwordx4 v[198:199], off
	v_lshl_add_u64 v[198:199], s[20:21], 0, v[208:209]
	s_add_i32 m0, s42, 0x2000
	s_nop 0
	global_load_lds_dwordx4 v[198:199], off
	v_lshl_add_u64 v[198:199], s[72:73], 0, v[204:205]
	s_mov_b32 m0, s19
	s_nop 0
	global_load_lds_dwordx4 v[198:199], off
	s_mov_b32 m0, s74
	s_nop 0
	global_load_lds_dwordx4 v[200:201], off
	s_waitcnt vmcnt(8)
	s_waitcnt lgkmcnt(0)
	s_barrier
; #define PG8_STAGE(bufoff, gbase, voff) do { _Pragma("unroll") for (int _i = 0; _i < 2; ++_i) \
;         __builtin_amdgcn_global_load_lds((const unsigned*)((const char*)(gbase) + (voff)[_i]), (LAS unsigned*)(lds + (bufoff) + ldsw + _i * 8192), 16, 0, 0); } while (0)
; #define PG8_LDA(dst, b, h) do { _Pragma("unroll") for (int m = 0; m < 4; ++m) _Pragma("unroll") for (int k = 0; k < 2; ++k) dst[m][k] = *(const LAS bf16x8*)(lds + PG8_SA(b, h) + aoff + m * 2048 + k * 1024); } while (0)
; #define PG8_LDB(dst, b, h) do { _Pragma("unroll") for (int n = 0; n < 2; ++n) _Pragma("unroll") for (int k = 0; k < 2; ++k) dst[n][k] = *(const LAS bf16x8*)(lds + PG8_SB(b, h) + boff + n * 2048 + k * 1024); } while (0)
; #define PG8_MMA(ai, bj, At, Bt) do { __builtin_amdgcn_s_setprio(1); _Pragma("unroll") for (int m = 0; m < 4; ++m) _Pragma("unroll") for (int n = 0; n < 2; ++n) _Pragma("unroll") for (int k = 0; k < 2; ++k) \
;         acc[ai][bj][m][n] = __builtin_amdgcn_mfma_f32_16x16x32_bf16(Bt[n][k], At[m][k], acc[ai][bj][m][n], 0, 0, 0); __builtin_amdgcn_s_setprio(0); } while (0)
; #define PG8_WAIT_V(n) asm volatile("s_waitcnt vmcnt(" #n ")" ::: "memory")
; #define PG8_WAIT_L(n) asm volatile("s_waitcnt lgkmcnt(" #n ")" ::: "memory")
; #define PG8_BAR __builtin_amdgcn_s_barrier()
; #define PG8_SCHED __builtin_amdgcn_sched_barrier(0)
; template <class Epi>
; __device__ __forceinline__ void gemm_phase(LAS unsigned char* lds, const Gemm g, const Sched& S, const Epi& E, const int tid) {
;     ...
;             PG8_WAIT_V(8); PG8_WAIT_L(0); PG8_BAR; PG8_MMA(1, 0, At, B0); PG8_MMA(1, 1, At, B1); PG8_BAR; PG8_SCHED;
;             PG8_LDB(B0, 1, 0); PG8_LDB(B1, 1, 1); PG8_SCHED; PG8_LDA(At, 1, 0); PG8_STAGE(PG8_SA(0, 1), a2 + hA, voffA);
;             PG8_WAIT_V(8); PG8_WAIT_L(0); PG8_BAR; PG8_MMA(0, 0, At, B0); PG8_MMA(0, 1, At, B1); PG8_BAR; PG8_SCHED;
	s_setprio 1
	s_waitcnt lgkmcnt(0)
	v_mfma_f32_16x16x32_bf16 v[60:63], v[104:107], v[160:163], 0
	v_mfma_f32_16x16x32_bf16 v[56:59], v[120:123], v[160:163], 0
	v_mfma_f32_16x16x32_bf16 v[44:47], v[104:107], v[168:171], 0
	v_mfma_f32_16x16x32_bf16 v[40:43], v[120:123], v[168:171], 0
	v_mfma_f32_16x16x32_bf16 v[28:31], v[104:107], v[176:179], 0
	v_mfma_f32_16x16x32_bf16 v[24:27], v[120:123], v[176:179], 0
	v_mfma_f32_16x16x32_bf16 v[12:15], v[104:107], v[184:187], 0
	v_mfma_f32_16x16x32_bf16 v[8:11], v[120:123], v[184:187], 0
	v_mfma_f32_16x16x32_bf16 v[60:63], v[112:115], v[164:167], v[60:63]
	v_mfma_f32_16x16x32_bf16 v[56:59], v[128:131], v[164:167], v[56:59]
	v_mfma_f32_16x16x32_bf16 v[44:47], v[112:115], v[172:175], v[44:47]
	v_mfma_f32_16x16x32_bf16 v[40:43], v[128:131], v[172:175], v[40:43]
	v_mfma_f32_16x16x32_bf16 v[28:31], v[112:115], v[180:183], v[28:31]
	v_mfma_f32_16x16x32_bf16 v[24:27], v[128:131], v[180:183], v[24:27]
	v_mfma_f32_16x16x32_bf16 v[12:15], v[112:115], v[188:191], v[12:15]
	v_mfma_f32_16x16x32_bf16 v[8:11], v[128:131], v[188:191], v[8:11]
	s_setprio 0
	s_setprio 1
	v_mfma_f32_16x16x32_bf16 v[52:55], v[136:139], v[160:163], 0
	v_mfma_f32_16x16x32_bf16 v[48:51], v[148:151], v[160:163], 0
	v_mfma_f32_16x16x32_bf16 v[36:39], v[136:139], v[168:171], 0
	v_mfma_f32_16x16x32_bf16 v[32:35], v[148:151], v[168:171], 0
	v_mfma_f32_16x16x32_bf16 v[20:23], v[136:139], v[176:179], 0
	v_mfma_f32_16x16x32_bf16 v[16:19], v[148:151], v[176:179], 0
	v_mfma_f32_16x16x32_bf16 v[4:7], v[136:139], v[184:187], 0
	v_mfma_f32_16x16x32_bf16 v[0:3], v[148:151], v[184:187], 0
	v_mfma_f32_16x16x32_bf16 v[52:55], v[140:143], v[164:167], v[52:55]
	v_mfma_f32_16x16x32_bf16 v[48:51], v[156:159], v[164:167], v[48:51]
	v_mfma_f32_16x16x32_bf16 v[36:39], v[140:143], v[172:175], v[36:39]
	v_mfma_f32_16x16x32_bf16 v[32:35], v[156:159], v[172:175], v[32:35]
	v_mfma_f32_16x16x32_bf16 v[20:23], v[140:143], v[180:183], v[20:23]
	v_mfma_f32_16x16x32_bf16 v[16:19], v[156:159], v[180:183], v[16:19]
	v_mfma_f32_16x16x32_bf16 v[4:7], v[140:143], v[188:191], v[4:7]
	v_mfma_f32_16x16x32_bf16 v[0:3], v[156:159], v[188:191], v[0:3]
	s_setprio 0
	s_barrier
	s_add_i32 s42, 0, 0x18000
	s_add_i32 s45, 0, 0x1c000
	v_add_u32_e32 v128, s42, v241
	v_add_u32_e32 v156, s45, v241
	ds_read_b128 v[104:107], v128
	ds_read_b128 v[112:115], v128 offset:1024
	ds_read_b128 v[120:123], v128 offset:2048
	ds_read_b128 v[128:131], v128 offset:3072
	ds_read_b128 v[136:139], v156
	ds_read_b128 v[140:143], v156 offset:1024
	ds_read_b128 v[148:151], v156 offset:2048
	ds_read_b128 v[156:159], v156 offset:3072
	s_add_u32 s20, s72, 0x120000
	s_addc_u32 s21, s73, 0
	s_mov_b32 m0, s75
	v_lshl_add_u64 v[214:215], s[20:21], 0, v[204:205]
	ds_read_b128 v[160:163], v243 offset:32768
	ds_read_b128 v[164:167], v243 offset:33792
	ds_read_b128 v[168:171], v243 offset:34816
	ds_read_b128 v[172:175], v243 offset:35840
	ds_read_b128 v[176:179], v243 offset:36864
	ds_read_b128 v[180:183], v243 offset:37888
	ds_read_b128 v[184:187], v243 offset:38912
	ds_read_b128 v[188:191], v243 offset:39936
	global_load_lds_dwordx4 v[214:215], off
	v_lshl_add_u64 v[214:215], s[20:21], 0, v[206:207]
	s_mov_b32 m0, s76
	s_nop 0
	global_load_lds_dwordx4 v[214:215], off
	s_waitcnt vmcnt(8)
	s_waitcnt lgkmcnt(0)
	s_barrier
	s_setprio 1
	s_waitcnt lgkmcnt(0)
	v_mfma_f32_16x16x32_bf16 v[152:155], v[104:107], v[160:163], v[152:155]
	v_mfma_f32_16x16x32_bf16 v[144:147], v[120:123], v[160:163], v[144:147]
	v_mfma_f32_16x16x32_bf16 v[116:119], v[104:107], v[168:171], v[116:119]
	v_mfma_f32_16x16x32_bf16 v[108:111], v[120:123], v[168:171], v[108:111]
	v_mfma_f32_16x16x32_bf16 v[92:95], v[104:107], v[176:179], v[92:95]
	v_mfma_f32_16x16x32_bf16 v[88:91], v[120:123], v[176:179], v[88:91]
	v_mfma_f32_16x16x32_bf16 v[76:79], v[104:107], v[184:187], v[76:79]
	v_mfma_f32_16x16x32_bf16 v[72:75], v[120:123], v[184:187], v[72:75]
	v_mfma_f32_16x16x32_bf16 v[152:155], v[112:115], v[164:167], v[152:155]
	v_mfma_f32_16x16x32_bf16 v[144:147], v[128:131], v[164:167], v[144:147]
	v_mfma_f32_16x16x32_bf16 v[116:119], v[112:115], v[172:175], v[116:119]
	v_mfma_f32_16x16x32_bf16 v[108:111], v[128:131], v[172:175], v[108:111]
	v_mfma_f32_16x16x32_bf16 v[92:95], v[112:115], v[180:183], v[92:95]
	v_mfma_f32_16x16x32_bf16 v[88:91], v[128:131], v[180:183], v[88:91]
	v_mfma_f32_16x16x32_bf16 v[76:79], v[112:115], v[188:191], v[76:79]
	v_mfma_f32_16x16x32_bf16 v[72:75], v[128:131], v[188:191], v[72:75]
	s_setprio 0
	s_setprio 1
	v_mfma_f32_16x16x32_bf16 v[132:135], v[136:139], v[160:163], v[132:135]
	v_mfma_f32_16x16x32_bf16 v[124:127], v[148:151], v[160:163], v[124:127]
	v_mfma_f32_16x16x32_bf16 v[100:103], v[136:139], v[168:171], v[100:103]
	v_mfma_f32_16x16x32_bf16 v[96:99], v[148:151], v[168:171], v[96:99]
	v_mfma_f32_16x16x32_bf16 v[84:87], v[136:139], v[176:179], v[84:87]
	v_mfma_f32_16x16x32_bf16 v[80:83], v[148:151], v[176:179], v[80:83]
	v_mfma_f32_16x16x32_bf16 v[68:71], v[136:139], v[184:187], v[68:71]
	v_mfma_f32_16x16x32_bf16 v[64:67], v[148:151], v[184:187], v[64:67]
	v_mfma_f32_16x16x32_bf16 v[132:135], v[140:143], v[164:167], v[132:135]
	v_mfma_f32_16x16x32_bf16 v[124:127], v[156:159], v[164:167], v[124:127]
	v_mfma_f32_16x16x32_bf16 v[100:103], v[140:143], v[172:175], v[100:103]
	v_mfma_f32_16x16x32_bf16 v[96:99], v[156:159], v[172:175], v[96:99]
	v_mfma_f32_16x16x32_bf16 v[84:87], v[140:143], v[180:183], v[84:87]
	v_mfma_f32_16x16x32_bf16 v[80:83], v[156:159], v[180:183], v[80:83]
	v_mfma_f32_16x16x32_bf16 v[68:71], v[140:143], v[188:191], v[68:71]
	v_mfma_f32_16x16x32_bf16 v[64:67], v[156:159], v[188:191], v[64:67]
	s_setprio 0
	s_barrier
; #define PG8_STAGE(bufoff, gbase, voff) do { _Pragma("unroll") for (int _i = 0; _i < 2; ++_i) \
;         __builtin_amdgcn_global_load_lds((const unsigned*)((const char*)(gbase) + (voff)[_i]), (LAS unsigned*)(lds + (bufoff) + ldsw + _i * 8192), 16, 0, 0); } while (0)
; #define PG8_LDA(dst, b, h) do { _Pragma("unroll") for (int m = 0; m < 4; ++m) _Pragma("unroll") for (int k = 0; k < 2; ++k) dst[m][k] = *(const LAS bf16x8*)(lds + PG8_SA(b, h) + aoff + m * 2048 + k * 1024); } while (0)
; #define PG8_MMA(ai, bj, At, Bt) do { __builtin_amdgcn_s_setprio(1); _Pragma("unroll") for (int m = 0; m < 4; ++m) _Pragma("unroll") for (int n = 0; n < 2; ++n) _Pragma("unroll") for (int k = 0; k < 2; ++k) \
;         acc[ai][bj][m][n] = __builtin_amdgcn_mfma_f32_16x16x32_bf16(Bt[n][k], At[m][k], acc[ai][bj][m][n], 0, 0, 0); __builtin_amdgcn_s_setprio(0); } while (0)
; #define PG8_WAIT_V(n) asm volatile("s_waitcnt vmcnt(" #n ")" ::: "memory")
; #define PG8_WAIT_L(n) asm volatile("s_waitcnt lgkmcnt(" #n ")" ::: "memory")
; #define PG8_BAR __builtin_amdgcn_s_barrier()
; #define PG8_SCHED __builtin_amdgcn_sched_barrier(0)
; template <class Epi>
; __device__ __forceinline__ void gemm_phase(LAS unsigned char* lds, const Gemm g, const Sched& S, const Epi& E, const int tid) {
;     ...
;             PG8_LDA(At, 1, 1); PG8_STAGE(PG8_SB(1, 0), b3, voffB); PG8_STAGE(PG8_SB(1, 1), b3 + hB, voffB); PG8_STAGE(PG8_SA(1, 0), a3, voffA);
;             PG8_WAIT_V(8); PG8_WAIT_L(0); PG8_BAR; PG8_MMA(1, 0, At, B0); PG8_MMA(1, 1, At, B1); PG8_BAR; PG8_SCHED;
;         }
	s_add_i32 s20, s42, s35
	v_lshl_add_u64 v[194:195], v[194:195], 0, s[94:95]
	s_mov_b32 m0, s20
	ds_read_b128 v[160:163], v243 offset:49152
	ds_read_b128 v[164:167], v243 offset:50176
	ds_read_b128 v[168:171], v243 offset:51200
	ds_read_b128 v[172:175], v243 offset:52224
	ds_read_b128 v[176:179], v243 offset:53248
	ds_read_b128 v[180:183], v243 offset:54272
	ds_read_b128 v[184:187], v243 offset:55296
	ds_read_b128 v[188:191], v243 offset:56320
	global_load_lds_dwordx4 v[194:195], off
	s_add_i32 m0, s20, 0x2000
	s_add_u32 s20, s22, 0x20080
	v_lshl_add_u64 v[194:195], v[196:197], 0, s[94:95]
	s_addc_u32 s21, s23, 0
	s_add_i32 s22, s45, s35
	global_load_lds_dwordx4 v[194:195], off
	v_lshl_add_u64 v[194:195], s[20:21], 0, v[192:193]
	s_mov_b32 m0, s22
	s_nop 0
	global_load_lds_dwordx4 v[194:195], off
	v_lshl_add_u64 v[194:195], s[20:21], 0, v[208:209]
	s_add_i32 m0, s22, 0x2000
	s_nop 0
	global_load_lds_dwordx4 v[194:195], off
	v_lshl_add_u64 v[194:195], v[198:199], 0, s[94:95]
	s_mov_b32 m0, s77
	s_nop 0
	global_load_lds_dwordx4 v[194:195], off
	v_lshl_add_u64 v[194:195], v[200:201], 0, s[94:95]
	s_mov_b32 m0, s78
	s_nop 0
	global_load_lds_dwordx4 v[194:195], off
	s_waitcnt vmcnt(8)
	s_waitcnt lgkmcnt(0)
	s_barrier
	s_setprio 1
	s_waitcnt lgkmcnt(0)
	v_mfma_f32_16x16x32_bf16 v[60:63], v[104:107], v[160:163], v[60:63]
	v_mfma_f32_16x16x32_bf16 v[56:59], v[120:123], v[160:163], v[56:59]
	v_mfma_f32_16x16x32_bf16 v[44:47], v[104:107], v[168:171], v[44:47]
	v_mfma_f32_16x16x32_bf16 v[40:43], v[120:123], v[168:171], v[40:43]
	v_mfma_f32_16x16x32_bf16 v[28:31], v[104:107], v[176:179], v[28:31]
	v_mfma_f32_16x16x32_bf16 v[24:27], v[120:123], v[176:179], v[24:27]
	v_mfma_f32_16x16x32_bf16 v[12:15], v[104:107], v[184:187], v[12:15]
	v_mfma_f32_16x16x32_bf16 v[8:11], v[120:123], v[184:187], v[8:11]
	v_mfma_f32_16x16x32_bf16 v[60:63], v[112:115], v[164:167], v[60:63]
	v_mfma_f32_16x16x32_bf16 v[56:59], v[128:131], v[164:167], v[56:59]
	v_mfma_f32_16x16x32_bf16 v[44:47], v[112:115], v[172:175], v[44:47]
	v_mfma_f32_16x16x32_bf16 v[40:43], v[128:131], v[172:175], v[40:43]
	v_mfma_f32_16x16x32_bf16 v[28:31], v[112:115], v[180:183], v[28:31]
	v_mfma_f32_16x16x32_bf16 v[24:27], v[128:131], v[180:183], v[24:27]
	v_mfma_f32_16x16x32_bf16 v[12:15], v[112:115], v[188:191], v[12:15]
	v_mfma_f32_16x16x32_bf16 v[8:11], v[128:131], v[188:191], v[8:11]
	s_setprio 0
	s_setprio 1
	v_mfma_f32_16x16x32_bf16 v[52:55], v[136:139], v[160:163], v[52:55]
	v_mfma_f32_16x16x32_bf16 v[48:51], v[148:151], v[160:163], v[48:51]
	v_mfma_f32_16x16x32_bf16 v[36:39], v[136:139], v[168:171], v[36:39]
	v_mfma_f32_16x16x32_bf16 v[32:35], v[148:151], v[168:171], v[32:35]
	v_mfma_f32_16x16x32_bf16 v[20:23], v[136:139], v[176:179], v[20:23]
	v_mfma_f32_16x16x32_bf16 v[16:19], v[148:151], v[176:179], v[16:19]
	v_mfma_f32_16x16x32_bf16 v[4:7], v[136:139], v[184:187], v[4:7]
	v_mfma_f32_16x16x32_bf16 v[0:3], v[148:151], v[184:187], v[0:3]
	v_mfma_f32_16x16x32_bf16 v[52:55], v[140:143], v[164:167], v[52:55]
	v_mfma_f32_16x16x32_bf16 v[48:51], v[156:159], v[164:167], v[48:51]
	v_mfma_f32_16x16x32_bf16 v[36:39], v[140:143], v[172:175], v[36:39]
	v_mfma_f32_16x16x32_bf16 v[32:35], v[156:159], v[172:175], v[32:35]
	v_mfma_f32_16x16x32_bf16 v[20:23], v[140:143], v[180:183], v[20:23]
	v_mfma_f32_16x16x32_bf16 v[16:19], v[156:159], v[180:183], v[16:19]
	v_mfma_f32_16x16x32_bf16 v[4:7], v[140:143], v[188:191], v[4:7]
	v_mfma_f32_16x16x32_bf16 v[0:3], v[156:159], v[188:191], v[0:3]
	s_setprio 0
	s_barrier
	s_add_i32 s40, s40, 2
	s_add_u32 s13, s13, 0x100
	s_addc_u32 s37, s37, 0
	s_cmp_gt_u32 s40, 5
	s_mov_b64 s[20:21], s[6:7]
	s_cbranch_scc1 .Lgk_exit_2

; #define PG8_STAGE(bufoff, gbase, voff) do { _Pragma("unroll") for (int _i = 0; _i < 2; ++_i) \
;         __builtin_amdgcn_global_load_lds((const unsigned*)((const char*)(gbase) + (voff)[_i]), (LAS unsigned*)(lds + (bufoff) + ldsw + _i * 8192), 16, 0, 0); } while (0)
; #define PG8_LDA(dst, b, h) do { _Pragma("unroll") for (int m = 0; m < 4; ++m) _Pragma("unroll") for (int k = 0; k < 2; ++k) dst[m][k] = *(const LAS bf16x8*)(lds + PG8_SA(b, h) + aoff + m * 2048 + k * 1024); } while (0)
; #define PG8_LDB(dst, b, h) do { _Pragma("unroll") for (int n = 0; n < 2; ++n) _Pragma("unroll") for (int k = 0; k < 2; ++k) dst[n][k] = *(const LAS bf16x8*)(lds + PG8_SB(b, h) + boff + n * 2048 + k * 1024); } while (0)
; #define PG8_MMA(ai, bj, At, Bt) do { __builtin_amdgcn_s_setprio(1); _Pragma("unroll") for (int m = 0; m < 4; ++m) _Pragma("unroll") for (int n = 0; n < 2; ++n) _Pragma("unroll") for (int k = 0; k < 2; ++k) \
;         acc[ai][bj][m][n] = __builtin_amdgcn_mfma_f32_16x16x32_bf16(Bt[n][k], At[m][k], acc[ai][bj][m][n], 0, 0, 0); __builtin_amdgcn_s_setprio(0); } while (0)
; #define PG8_WAIT_V(n) asm volatile("s_waitcnt vmcnt(" #n ")" ::: "memory")
; #define PG8_WAIT_L(n) asm volatile("s_waitcnt lgkmcnt(" #n ")" ::: "memory")
; #define PG8_BAR __builtin_amdgcn_s_barrier()
; #define PG8_SCHED __builtin_amdgcn_sched_barrier(0)
; template <class Epi>
; __device__ __forceinline__ void gemm_phase(LAS unsigned char* lds, const Gemm g, const Sched& S, const Epi& E, const int tid) {
;     ...
;         for (int t = 0; t < nt; t += 2) {
;             const bool last = (t == nt - 2);
;             const char* a1 = cA + (size_t)(t + 1) * kstep;
;             const char* a2 = last ? nA : cA + (size_t)(t + 2) * kstep; const char* b2 = last ? nB : cB + (size_t)(t + 2) * kstep;
;             const char* a3 = a2 + kstep; const char* b3 = b2 + kstep;
;             PG8_LDB(B0, 0, 0); PG8_LDB(B1, 0, 1); PG8_SCHED; PG8_LDA(At, 0, 0); PG8_STAGE(PG8_SA(1, 1), a1 + hA, voffA);
;             PG8_WAIT_V(8); PG8_WAIT_L(0); PG8_BAR; PG8_MMA(0, 0, At, B0); PG8_MMA(0, 1, At, B1); PG8_BAR; PG8_SCHED;
;             PG8_LDA(At, 0, 1); PG8_STAGE(PG8_SB(0, 0), b2, voffB); PG8_STAGE(PG8_SB(0, 1), b2 + hB, voffB); PG8_STAGE(PG8_SA(0, 0), a2, voffA);
.LBB0_1142:
	s_add_u32 s17, s22, 0x100
	s_addc_u32 vcc_lo, s23, 0
	s_mov_b32 vcc_hi, -2
	s_add_u32 s22, s20, 0x100
	s_addc_u32 s23, s21, 0
	s_add_i32 s43, 0, 0x10000
	s_cmp_eq_u32 vcc_hi, 12
	s_cselect_b32 s75, s7, s23
	s_cselect_b32 s74, s6, s22
	s_cselect_b32 s73, s19, vcc_lo
	s_cselect_b32 s72, s18, s17
	s_add_i32 s44, 0, 0x14000
	v_add_u32_e32 v100, s43, v159
	v_add_u32_e32 v170, s44, v159
	ds_read_b128 v[64:67], v100
	ds_read_b128 v[68:71], v100 offset:1024
	ds_read_b128 v[72:75], v100 offset:2048
	ds_read_b128 v[100:103], v100 offset:3072
	ds_read_b128 v[154:157], v170
	ds_read_b128 v[162:165], v170 offset:1024
	ds_read_b128 v[166:169], v170 offset:2048
	ds_read_b128 v[170:173], v170 offset:3072
	v_lshl_add_u64 v[190:191], s[20:21], 0, v[150:151]
	s_add_i32 m0, s80, 0xc000
	ds_read_b128 v[174:177], v161
	ds_read_b128 v[178:181], v161 offset:1024
	ds_read_b128 v[182:185], v161 offset:2048
	ds_read_b128 v[186:189], v161 offset:3072
	ds_read_b128 v[194:197], v161 offset:4096
	ds_read_b128 v[198:201], v161 offset:5120
	ds_read_b128 v[204:207], v161 offset:6144
	ds_read_b128 v[208:211], v161 offset:7168
	global_load_lds_dwordx4 v[190:191], off
	v_lshl_add_u64 v[190:191], s[20:21], 0, v[152:153]
	s_add_i32 m0, s80, 0xe000
	s_nop 0
	global_load_lds_dwordx4 v[190:191], off
	s_waitcnt vmcnt(8)
	s_waitcnt lgkmcnt(0)
	s_barrier
	s_setprio 1
	s_waitcnt lgkmcnt(0)
	v_mfma_f32_16x16x32_bf16 v[140:143], v[64:67], v[174:177], 0
	v_mfma_f32_16x16x32_bf16 v[136:139], v[72:75], v[174:177], 0
	v_mfma_f32_16x16x32_bf16 v[132:135], v[64:67], v[182:185], 0
	v_mfma_f32_16x16x32_bf16 v[120:123], v[72:75], v[182:185], 0
	v_mfma_f32_16x16x32_bf16 v[108:111], v[64:67], v[194:197], 0
	v_mfma_f32_16x16x32_bf16 v[104:107], v[72:75], v[194:197], 0
	v_mfma_f32_16x16x32_bf16 v[96:99], v[64:67], v[204:207], 0
	v_mfma_f32_16x16x32_bf16 v[84:87], v[72:75], v[204:207], 0
	v_mfma_f32_16x16x32_bf16 v[140:143], v[68:71], v[178:181], v[140:143]
	v_mfma_f32_16x16x32_bf16 v[136:139], v[100:103], v[178:181], v[136:139]
	v_mfma_f32_16x16x32_bf16 v[132:135], v[68:71], v[186:189], v[132:135]
	v_mfma_f32_16x16x32_bf16 v[120:123], v[100:103], v[186:189], v[120:123]
	v_mfma_f32_16x16x32_bf16 v[108:111], v[68:71], v[198:201], v[108:111]
	v_mfma_f32_16x16x32_bf16 v[104:107], v[100:103], v[198:201], v[104:107]
	v_mfma_f32_16x16x32_bf16 v[96:99], v[68:71], v[208:211], v[96:99]
	v_mfma_f32_16x16x32_bf16 v[84:87], v[100:103], v[208:211], v[84:87]
	s_setprio 0
	s_setprio 1
	v_mfma_f32_16x16x32_bf16 v[128:131], v[154:157], v[174:177], 0
	v_mfma_f32_16x16x32_bf16 v[124:127], v[166:169], v[174:177], 0
	v_mfma_f32_16x16x32_bf16 v[116:119], v[154:157], v[182:185], 0
	v_mfma_f32_16x16x32_bf16 v[112:115], v[166:169], v[182:185], 0
	v_mfma_f32_16x16x32_bf16 v[92:95], v[154:157], v[194:197], 0
	v_mfma_f32_16x16x32_bf16 v[88:91], v[166:169], v[194:197], 0
	v_mfma_f32_16x16x32_bf16 v[80:83], v[154:157], v[204:207], 0
	v_mfma_f32_16x16x32_bf16 v[76:79], v[166:169], v[204:207], 0
	v_mfma_f32_16x16x32_bf16 v[128:131], v[162:165], v[178:181], v[128:131]
	v_mfma_f32_16x16x32_bf16 v[124:127], v[170:173], v[178:181], v[124:127]
	v_mfma_f32_16x16x32_bf16 v[116:119], v[162:165], v[186:189], v[116:119]
	v_mfma_f32_16x16x32_bf16 v[112:115], v[170:173], v[186:189], v[112:115]
	v_mfma_f32_16x16x32_bf16 v[92:95], v[162:165], v[198:201], v[92:95]
	v_mfma_f32_16x16x32_bf16 v[88:91], v[170:173], v[198:201], v[88:91]
	v_mfma_f32_16x16x32_bf16 v[80:83], v[162:165], v[208:211], v[80:83]
	v_mfma_f32_16x16x32_bf16 v[76:79], v[170:173], v[208:211], v[76:79]
	s_setprio 0
	s_barrier
	s_add_i32 s20, s43, s76
	v_lshl_add_u64 v[190:191], s[72:73], 0, v[192:193]
	s_mov_b32 m0, s20
	ds_read_b128 v[174:177], v161 offset:16384
	ds_read_b128 v[178:181], v161 offset:17408
	ds_read_b128 v[182:185], v161 offset:18432
	ds_read_b128 v[186:189], v161 offset:19456
	ds_read_b128 v[194:197], v161 offset:20480
	ds_read_b128 v[198:201], v161 offset:21504
	ds_read_b128 v[204:207], v161 offset:22528
	ds_read_b128 v[208:211], v161 offset:23552
	global_load_lds_dwordx4 v[190:191], off
	s_add_i32 m0, s20, 0x2000
	s_add_u32 s20, s72, 0x40000
	v_lshl_add_u64 v[212:213], s[72:73], 0, v[144:145]
	s_addc_u32 s21, s73, 0
	s_add_i32 s43, s44, s76
	global_load_lds_dwordx4 v[212:213], off
	v_lshl_add_u64 v[214:215], s[20:21], 0, v[192:193]
	s_mov_b32 m0, s43
	v_lshl_add_u64 v[216:217], s[74:75], 0, v[146:147]
	global_load_lds_dwordx4 v[214:215], off
	v_lshl_add_u64 v[214:215], s[20:21], 0, v[144:145]
	s_add_i32 m0, s43, 0x2000
	s_nop 0
	global_load_lds_dwordx4 v[214:215], off
	v_lshl_add_u64 v[214:215], s[74:75], 0, v[148:149]
	s_mov_b32 m0, s80
	s_nop 0
	global_load_lds_dwordx4 v[214:215], off
	s_mov_b32 m0, s81
	s_nop 0
	global_load_lds_dwordx4 v[216:217], off
	s_waitcnt vmcnt(8)
	s_waitcnt lgkmcnt(0)
	s_barrier
; #define PG8_STAGE(bufoff, gbase, voff) do { _Pragma("unroll") for (int _i = 0; _i < 2; ++_i) \
;         __builtin_amdgcn_global_load_lds((const unsigned*)((const char*)(gbase) + (voff)[_i]), (LAS unsigned*)(lds + (bufoff) + ldsw + _i * 8192), 16, 0, 0); } while (0)
; #define PG8_LDA(dst, b, h) do { _Pragma("unroll") for (int m = 0; m < 4; ++m) _Pragma("unroll") for (int k = 0; k < 2; ++k) dst[m][k] = *(const LAS bf16x8*)(lds + PG8_SA(b, h) + aoff + m * 2048 + k * 1024); } while (0)
; #define PG8_LDB(dst, b, h) do { _Pragma("unroll") for (int n = 0; n < 2; ++n) _Pragma("unroll") for (int k = 0; k < 2; ++k) dst[n][k] = *(const LAS bf16x8*)(lds + PG8_SB(b, h) + boff + n * 2048 + k * 1024); } while (0)
; #define PG8_MMA(ai, bj, At, Bt) do { __builtin_amdgcn_s_setprio(1); _Pragma("unroll") for (int m = 0; m < 4; ++m) _Pragma("unroll") for (int n = 0; n < 2; ++n) _Pragma("unroll") for (int k = 0; k < 2; ++k) \
;         acc[ai][bj][m][n] = __builtin_amdgcn_mfma_f32_16x16x32_bf16(Bt[n][k], At[m][k], acc[ai][bj][m][n], 0, 0, 0); __builtin_amdgcn_s_setprio(0); } while (0)
; #define PG8_WAIT_V(n) asm volatile("s_waitcnt vmcnt(" #n ")" ::: "memory")
; #define PG8_WAIT_L(n) asm volatile("s_waitcnt lgkmcnt(" #n ")" ::: "memory")
; #define PG8_BAR __builtin_amdgcn_s_barrier()
; #define PG8_SCHED __builtin_amdgcn_sched_barrier(0)
; template <class Epi>
; __device__ __forceinline__ void gemm_phase(LAS unsigned char* lds, const Gemm g, const Sched& S, const Epi& E, const int tid) {
;     ...
;             PG8_WAIT_V(8); PG8_WAIT_L(0); PG8_BAR; PG8_MMA(1, 0, At, B0); PG8_MMA(1, 1, At, B1); PG8_BAR; PG8_SCHED;
;             PG8_LDB(B0, 1, 0); PG8_LDB(B1, 1, 1); PG8_SCHED; PG8_LDA(At, 1, 0); PG8_STAGE(PG8_SA(0, 1), a2 + hA, voffA);
;             PG8_WAIT_V(8); PG8_WAIT_L(0); PG8_BAR; PG8_MMA(0, 0, At, B0); PG8_MMA(0, 1, At, B1); PG8_BAR; PG8_SCHED;
	s_setprio 1
	s_waitcnt lgkmcnt(0)
	v_mfma_f32_16x16x32_bf16 v[60:63], v[64:67], v[174:177], 0
	v_mfma_f32_16x16x32_bf16 v[56:59], v[72:75], v[174:177], 0
	v_mfma_f32_16x16x32_bf16 v[52:55], v[64:67], v[182:185], 0
	v_mfma_f32_16x16x32_bf16 v[40:43], v[72:75], v[182:185], 0
	v_mfma_f32_16x16x32_bf16 v[28:31], v[64:67], v[194:197], 0
	v_mfma_f32_16x16x32_bf16 v[24:27], v[72:75], v[194:197], 0
	v_mfma_f32_16x16x32_bf16 v[20:23], v[64:67], v[204:207], 0
	v_mfma_f32_16x16x32_bf16 v[8:11], v[72:75], v[204:207], 0
	v_mfma_f32_16x16x32_bf16 v[60:63], v[68:71], v[178:181], v[60:63]
	v_mfma_f32_16x16x32_bf16 v[56:59], v[100:103], v[178:181], v[56:59]
	v_mfma_f32_16x16x32_bf16 v[52:55], v[68:71], v[186:189], v[52:55]
	v_mfma_f32_16x16x32_bf16 v[40:43], v[100:103], v[186:189], v[40:43]
	v_mfma_f32_16x16x32_bf16 v[28:31], v[68:71], v[198:201], v[28:31]
	v_mfma_f32_16x16x32_bf16 v[24:27], v[100:103], v[198:201], v[24:27]
	v_mfma_f32_16x16x32_bf16 v[20:23], v[68:71], v[208:211], v[20:23]
	v_mfma_f32_16x16x32_bf16 v[8:11], v[100:103], v[208:211], v[8:11]
	s_setprio 0
	s_setprio 1
	v_mfma_f32_16x16x32_bf16 v[48:51], v[154:157], v[174:177], 0
	v_mfma_f32_16x16x32_bf16 v[44:47], v[166:169], v[174:177], 0
	v_mfma_f32_16x16x32_bf16 v[36:39], v[154:157], v[182:185], 0
	v_mfma_f32_16x16x32_bf16 v[32:35], v[166:169], v[182:185], 0
	v_mfma_f32_16x16x32_bf16 v[16:19], v[154:157], v[194:197], 0
	v_mfma_f32_16x16x32_bf16 v[12:15], v[166:169], v[194:197], 0
	v_mfma_f32_16x16x32_bf16 v[4:7], v[154:157], v[204:207], 0
	v_mfma_f32_16x16x32_bf16 v[0:3], v[166:169], v[204:207], 0
	v_mfma_f32_16x16x32_bf16 v[48:51], v[162:165], v[178:181], v[48:51]
	v_mfma_f32_16x16x32_bf16 v[44:47], v[170:173], v[178:181], v[44:47]
	v_mfma_f32_16x16x32_bf16 v[36:39], v[162:165], v[186:189], v[36:39]
	v_mfma_f32_16x16x32_bf16 v[32:35], v[170:173], v[186:189], v[32:35]
	v_mfma_f32_16x16x32_bf16 v[16:19], v[162:165], v[198:201], v[16:19]
	v_mfma_f32_16x16x32_bf16 v[12:15], v[170:173], v[198:201], v[12:15]
	v_mfma_f32_16x16x32_bf16 v[4:7], v[162:165], v[208:211], v[4:7]
	v_mfma_f32_16x16x32_bf16 v[0:3], v[170:173], v[208:211], v[0:3]
	s_setprio 0
	s_barrier
	s_add_i32 s43, 0, 0x18000
	s_add_i32 s44, 0, 0x1c000
	v_add_u32_e32 v100, s43, v159
	v_add_u32_e32 v170, s44, v159
	ds_read_b128 v[64:67], v100
	ds_read_b128 v[68:71], v100 offset:1024
	ds_read_b128 v[72:75], v100 offset:2048
	ds_read_b128 v[100:103], v100 offset:3072
	ds_read_b128 v[154:157], v170
	ds_read_b128 v[162:165], v170 offset:1024
	ds_read_b128 v[166:169], v170 offset:2048
	ds_read_b128 v[170:173], v170 offset:3072
	s_add_u32 s20, s74, 0x120000
	s_addc_u32 s21, s75, 0
	s_mov_b32 m0, s3
	v_lshl_add_u64 v[218:219], s[20:21], 0, v[148:149]
	ds_read_b128 v[174:177], v161 offset:32768
	ds_read_b128 v[178:181], v161 offset:33792
	ds_read_b128 v[182:185], v161 offset:34816
	ds_read_b128 v[186:189], v161 offset:35840
	ds_read_b128 v[194:197], v161 offset:36864
	ds_read_b128 v[198:201], v161 offset:37888
	ds_read_b128 v[204:207], v161 offset:38912
	ds_read_b128 v[208:211], v161 offset:39936
	global_load_lds_dwordx4 v[218:219], off
	v_lshl_add_u64 v[218:219], s[20:21], 0, v[146:147]
	s_mov_b32 m0, s34
	s_nop 0
	global_load_lds_dwordx4 v[218:219], off
	s_waitcnt vmcnt(8)
	s_waitcnt lgkmcnt(0)
	s_barrier
	s_setprio 1
	s_waitcnt lgkmcnt(0)
	v_mfma_f32_16x16x32_bf16 v[140:143], v[64:67], v[174:177], v[140:143]
	v_mfma_f32_16x16x32_bf16 v[136:139], v[72:75], v[174:177], v[136:139]
	v_mfma_f32_16x16x32_bf16 v[132:135], v[64:67], v[182:185], v[132:135]
	v_mfma_f32_16x16x32_bf16 v[120:123], v[72:75], v[182:185], v[120:123]
	v_mfma_f32_16x16x32_bf16 v[108:111], v[64:67], v[194:197], v[108:111]
	v_mfma_f32_16x16x32_bf16 v[104:107], v[72:75], v[194:197], v[104:107]
	v_mfma_f32_16x16x32_bf16 v[96:99], v[64:67], v[204:207], v[96:99]
	v_mfma_f32_16x16x32_bf16 v[84:87], v[72:75], v[204:207], v[84:87]
	v_mfma_f32_16x16x32_bf16 v[140:143], v[68:71], v[178:181], v[140:143]
	v_mfma_f32_16x16x32_bf16 v[136:139], v[100:103], v[178:181], v[136:139]
	v_mfma_f32_16x16x32_bf16 v[132:135], v[68:71], v[186:189], v[132:135]
	v_mfma_f32_16x16x32_bf16 v[120:123], v[100:103], v[186:189], v[120:123]
	v_mfma_f32_16x16x32_bf16 v[108:111], v[68:71], v[198:201], v[108:111]
	v_mfma_f32_16x16x32_bf16 v[104:107], v[100:103], v[198:201], v[104:107]
	v_mfma_f32_16x16x32_bf16 v[96:99], v[68:71], v[208:211], v[96:99]
	v_mfma_f32_16x16x32_bf16 v[84:87], v[100:103], v[208:211], v[84:87]
	s_setprio 0
	s_setprio 1
	v_mfma_f32_16x16x32_bf16 v[128:131], v[154:157], v[174:177], v[128:131]
	v_mfma_f32_16x16x32_bf16 v[124:127], v[166:169], v[174:177], v[124:127]
	v_mfma_f32_16x16x32_bf16 v[116:119], v[154:157], v[182:185], v[116:119]
	v_mfma_f32_16x16x32_bf16 v[112:115], v[166:169], v[182:185], v[112:115]
	v_mfma_f32_16x16x32_bf16 v[92:95], v[154:157], v[194:197], v[92:95]
	v_mfma_f32_16x16x32_bf16 v[88:91], v[166:169], v[194:197], v[88:91]
	v_mfma_f32_16x16x32_bf16 v[80:83], v[154:157], v[204:207], v[80:83]
	v_mfma_f32_16x16x32_bf16 v[76:79], v[166:169], v[204:207], v[76:79]
	v_mfma_f32_16x16x32_bf16 v[128:131], v[162:165], v[178:181], v[128:131]
	v_mfma_f32_16x16x32_bf16 v[124:127], v[170:173], v[178:181], v[124:127]
	v_mfma_f32_16x16x32_bf16 v[116:119], v[162:165], v[186:189], v[116:119]
	v_mfma_f32_16x16x32_bf16 v[112:115], v[170:173], v[186:189], v[112:115]
	v_mfma_f32_16x16x32_bf16 v[92:95], v[162:165], v[198:201], v[92:95]
	v_mfma_f32_16x16x32_bf16 v[88:91], v[170:173], v[198:201], v[88:91]
	v_mfma_f32_16x16x32_bf16 v[80:83], v[162:165], v[208:211], v[80:83]
	v_mfma_f32_16x16x32_bf16 v[76:79], v[170:173], v[208:211], v[76:79]
	s_setprio 0
	s_barrier
; #define PG8_STAGE(bufoff, gbase, voff) do { _Pragma("unroll") for (int _i = 0; _i < 2; ++_i) \
;         __builtin_amdgcn_global_load_lds((const unsigned*)((const char*)(gbase) + (voff)[_i]), (LAS unsigned*)(lds + (bufoff) + ldsw + _i * 8192), 16, 0, 0); } while (0)
; #define PG8_LDA(dst, b, h) do { _Pragma("unroll") for (int m = 0; m < 4; ++m) _Pragma("unroll") for (int k = 0; k < 2; ++k) dst[m][k] = *(const LAS bf16x8*)(lds + PG8_SA(b, h) + aoff + m * 2048 + k * 1024); } while (0)
; #define PG8_MMA(ai, bj, At, Bt) do { __builtin_amdgcn_s_setprio(1); _Pragma("unroll") for (int m = 0; m < 4; ++m) _Pragma("unroll") for (int n = 0; n < 2; ++n) _Pragma("unroll") for (int k = 0; k < 2; ++k) \
;         acc[ai][bj][m][n] = __builtin_amdgcn_mfma_f32_16x16x32_bf16(Bt[n][k], At[m][k], acc[ai][bj][m][n], 0, 0, 0); __builtin_amdgcn_s_setprio(0); } while (0)
; #define PG8_WAIT_V(n) asm volatile("s_waitcnt vmcnt(" #n ")" ::: "memory")
; #define PG8_WAIT_L(n) asm volatile("s_waitcnt lgkmcnt(" #n ")" ::: "memory")
; #define PG8_BAR __builtin_amdgcn_s_barrier()
; #define PG8_SCHED __builtin_amdgcn_sched_barrier(0)
; template <class Epi>
; __device__ __forceinline__ void gemm_phase(LAS unsigned char* lds, const Gemm g, const Sched& S, const Epi& E, const int tid) {
;     ...
;             PG8_LDA(At, 1, 1); PG8_STAGE(PG8_SB(1, 0), b3, voffB); PG8_STAGE(PG8_SB(1, 1), b3 + hB, voffB); PG8_STAGE(PG8_SA(1, 0), a3, voffA);
;             PG8_WAIT_V(8); PG8_WAIT_L(0); PG8_BAR; PG8_MMA(1, 0, At, B0); PG8_MMA(1, 1, At, B1); PG8_BAR; PG8_SCHED;
;         }
	s_add_i32 s20, s43, s76
	v_lshl_add_u64 v[190:191], v[190:191], 0, s[94:95]
	s_mov_b32 m0, s20
	ds_read_b128 v[174:177], v161 offset:49152
	ds_read_b128 v[178:181], v161 offset:50176
	ds_read_b128 v[182:185], v161 offset:51200
	ds_read_b128 v[186:189], v161 offset:52224
	ds_read_b128 v[194:197], v161 offset:53248
	ds_read_b128 v[198:201], v161 offset:54272
	ds_read_b128 v[204:207], v161 offset:55296
	ds_read_b128 v[208:211], v161 offset:56320
	global_load_lds_dwordx4 v[190:191], off
	s_add_i32 m0, s20, 0x2000
	s_add_u32 s20, s72, 0x40080
	v_lshl_add_u64 v[190:191], v[212:213], 0, s[94:95]
	s_addc_u32 s21, s73, 0
	s_add_i32 s43, s44, s76
	global_load_lds_dwordx4 v[190:191], off
	v_lshl_add_u64 v[190:191], s[20:21], 0, v[192:193]
	s_mov_b32 m0, s43
	s_nop 0
	global_load_lds_dwordx4 v[190:191], off
	v_lshl_add_u64 v[190:191], s[20:21], 0, v[144:145]
	s_add_i32 m0, s43, 0x2000
	s_nop 0
	global_load_lds_dwordx4 v[190:191], off
	v_lshl_add_u64 v[190:191], v[214:215], 0, s[94:95]
	s_mov_b32 m0, s47
	s_nop 0
	global_load_lds_dwordx4 v[190:191], off
	v_lshl_add_u64 v[190:191], v[216:217], 0, s[94:95]
	s_mov_b32 m0, s40
	s_nop 0
	global_load_lds_dwordx4 v[190:191], off
	s_waitcnt vmcnt(8)
	s_waitcnt lgkmcnt(0)
	s_barrier
	s_setprio 1
	s_waitcnt lgkmcnt(0)
	v_mfma_f32_16x16x32_bf16 v[60:63], v[64:67], v[174:177], v[60:63]
	v_mfma_f32_16x16x32_bf16 v[56:59], v[72:75], v[174:177], v[56:59]
	v_mfma_f32_16x16x32_bf16 v[52:55], v[64:67], v[182:185], v[52:55]
	v_mfma_f32_16x16x32_bf16 v[40:43], v[72:75], v[182:185], v[40:43]
	v_mfma_f32_16x16x32_bf16 v[28:31], v[64:67], v[194:197], v[28:31]
	v_mfma_f32_16x16x32_bf16 v[24:27], v[72:75], v[194:197], v[24:27]
	v_mfma_f32_16x16x32_bf16 v[20:23], v[64:67], v[204:207], v[20:23]
	v_mfma_f32_16x16x32_bf16 v[8:11], v[72:75], v[204:207], v[8:11]
	v_mfma_f32_16x16x32_bf16 v[60:63], v[68:71], v[178:181], v[60:63]
	v_mfma_f32_16x16x32_bf16 v[56:59], v[100:103], v[178:181], v[56:59]
	v_mfma_f32_16x16x32_bf16 v[52:55], v[68:71], v[186:189], v[52:55]
	v_mfma_f32_16x16x32_bf16 v[40:43], v[100:103], v[186:189], v[40:43]
	v_mfma_f32_16x16x32_bf16 v[28:31], v[68:71], v[198:201], v[28:31]
	v_mfma_f32_16x16x32_bf16 v[24:27], v[100:103], v[198:201], v[24:27]
	v_mfma_f32_16x16x32_bf16 v[20:23], v[68:71], v[208:211], v[20:23]
	v_mfma_f32_16x16x32_bf16 v[8:11], v[100:103], v[208:211], v[8:11]
	s_setprio 0
	s_setprio 1
	v_mfma_f32_16x16x32_bf16 v[48:51], v[154:157], v[174:177], v[48:51]
	v_mfma_f32_16x16x32_bf16 v[44:47], v[166:169], v[174:177], v[44:47]
	v_mfma_f32_16x16x32_bf16 v[36:39], v[154:157], v[182:185], v[36:39]
	v_mfma_f32_16x16x32_bf16 v[32:35], v[166:169], v[182:185], v[32:35]
	v_mfma_f32_16x16x32_bf16 v[16:19], v[154:157], v[194:197], v[16:19]
	v_mfma_f32_16x16x32_bf16 v[12:15], v[166:169], v[194:197], v[12:15]
	v_mfma_f32_16x16x32_bf16 v[4:7], v[154:157], v[204:207], v[4:7]
	v_mfma_f32_16x16x32_bf16 v[0:3], v[166:169], v[204:207], v[0:3]
	v_mfma_f32_16x16x32_bf16 v[48:51], v[162:165], v[178:181], v[48:51]
	v_mfma_f32_16x16x32_bf16 v[44:47], v[170:173], v[178:181], v[44:47]
	v_mfma_f32_16x16x32_bf16 v[36:39], v[162:165], v[186:189], v[36:39]
	v_mfma_f32_16x16x32_bf16 v[32:35], v[170:173], v[186:189], v[32:35]
	v_mfma_f32_16x16x32_bf16 v[16:19], v[162:165], v[198:201], v[16:19]
	v_mfma_f32_16x16x32_bf16 v[12:15], v[170:173], v[198:201], v[12:15]
	v_mfma_f32_16x16x32_bf16 v[4:7], v[162:165], v[208:211], v[4:7]
	v_mfma_f32_16x16x32_bf16 v[0:3], v[170:173], v[208:211], v[0:3]
	s_setprio 0
	s_barrier
	s_add_i32 vcc_hi, vcc_hi, 2
	s_add_u32 s17, s17, 0x100
	s_addc_u32 vcc_lo, vcc_lo, 0
	s_cmp_gt_u32 vcc_hi, 13
	s_mov_b64 s[20:21], s[22:23]
	s_cbranch_scc1 .Lgk_exit_3

; #define PG8_BAR __builtin_amdgcn_s_barrier()
; template <class Epi>
; __device__ __forceinline__ void gemm_phase(LAS unsigned char* lds, const Gemm g, const Sched& S, const Epi& E, const int tid) {
;     ...
;         if (wr == 0) PG8_BAR;
.Lgk_exit_3:
	s_and_b64 vcc, exec, s[14:15]
	s_cbranch_vccz .LBB0_1146
	s_barrier

; #define PG8_STAGE(bufoff, gbase, voff) do { _Pragma("unroll") for (int _i = 0; _i < 2; ++_i) \
;         __builtin_amdgcn_global_load_lds((const unsigned*)((const char*)(gbase) + (voff)[_i]), (LAS unsigned*)(lds + (bufoff) + ldsw + _i * 8192), 16, 0, 0); } while (0)
; #define PG8_LDA(dst, b, h) do { _Pragma("unroll") for (int m = 0; m < 4; ++m) _Pragma("unroll") for (int k = 0; k < 2; ++k) dst[m][k] = *(const LAS bf16x8*)(lds + PG8_SA(b, h) + aoff + m * 2048 + k * 1024); } while (0)
; #define PG8_LDB(dst, b, h) do { _Pragma("unroll") for (int n = 0; n < 2; ++n) _Pragma("unroll") for (int k = 0; k < 2; ++k) dst[n][k] = *(const LAS bf16x8*)(lds + PG8_SB(b, h) + boff + n * 2048 + k * 1024); } while (0)
; #define PG8_MMA(ai, bj, At, Bt) do { __builtin_amdgcn_s_setprio(1); _Pragma("unroll") for (int m = 0; m < 4; ++m) _Pragma("unroll") for (int n = 0; n < 2; ++n) _Pragma("unroll") for (int k = 0; k < 2; ++k) \
;         acc[ai][bj][m][n] = __builtin_amdgcn_mfma_f32_16x16x32_bf16(Bt[n][k], At[m][k], acc[ai][bj][m][n], 0, 0, 0); __builtin_amdgcn_s_setprio(0); } while (0)
; #define PG8_WAIT_V(n) asm volatile("s_waitcnt vmcnt(" #n ")" ::: "memory")
; #define PG8_WAIT_L(n) asm volatile("s_waitcnt lgkmcnt(" #n ")" ::: "memory")
; #define PG8_BAR __builtin_amdgcn_s_barrier()
; #define PG8_SCHED __builtin_amdgcn_sched_barrier(0)
; template <class Epi>
; __device__ __forceinline__ void gemm_phase(LAS unsigned char* lds, const Gemm g, const Sched& S, const Epi& E, const int tid) {
;     ...
;         for (int t = 0; t < nt; t += 2) {
;             const bool last = (t == nt - 2);
;             const char* a1 = cA + (size_t)(t + 1) * kstep;
;             const char* a2 = last ? nA : cA + (size_t)(t + 2) * kstep; const char* b2 = last ? nB : cB + (size_t)(t + 2) * kstep;
;             const char* a3 = a2 + kstep; const char* b3 = b2 + kstep;
;             PG8_LDB(B0, 0, 0); PG8_LDB(B1, 0, 1); PG8_SCHED; PG8_LDA(At, 0, 0); PG8_STAGE(PG8_SA(1, 1), a1 + hA, voffA);
;             PG8_WAIT_V(8); PG8_WAIT_L(0); PG8_BAR; PG8_MMA(0, 0, At, B0); PG8_MMA(0, 1, At, B1); PG8_BAR; PG8_SCHED;
;             PG8_LDA(At, 0, 1); PG8_STAGE(PG8_SB(0, 0), b2, voffB); PG8_STAGE(PG8_SB(0, 1), b2 + hB, voffB); PG8_STAGE(PG8_SA(0, 0), a2, voffA);
.LBB0_1335:
	s_add_u32 s20, s20, 0x40080
	s_addc_u32 s21, s21, 0
	s_add_u32 s13, s22, 0x100
	s_addc_u32 s15, s23, 0
	s_mov_b32 s42, -2
	s_add_u32 s22, s20, 0xfffc0080
	s_addc_u32 s23, s21, -1
	s_add_i32 s43, 0, 0x10000
	s_cmp_eq_u32 s42, 12
	s_cselect_b32 s73, s7, s23
	s_cselect_b32 s72, s6, s22
	v_add_u32_e32 v138, s43, v141
	s_cselect_b32 s23, s17, s15
	s_cselect_b32 s22, s16, s13
	s_add_i32 s44, 0, 0x14000
	ds_read_b128 v[144:147], v138
	ds_read_b128 v[148:151], v138 offset:1024
	ds_read_b128 v[152:155], v138 offset:2048
	ds_read_b128 v[156:159], v138 offset:3072
	v_add_u32_e32 v138, s44, v141
	ds_read_b128 v[160:163], v138
	ds_read_b128 v[164:167], v138 offset:1024
	ds_read_b128 v[168:171], v138 offset:2048
	ds_read_b128 v[172:175], v138 offset:3072
	v_lshl_add_u64 v[138:139], s[20:21], 0, v[134:135]
	s_add_i32 m0, s19, 0xc000
	ds_read_b128 v[176:179], v143
	ds_read_b128 v[180:183], v143 offset:1024
	ds_read_b128 v[184:187], v143 offset:2048
	ds_read_b128 v[188:191], v143 offset:3072
	ds_read_b128 v[194:197], v143 offset:4096
	ds_read_b128 v[198:201], v143 offset:5120
	ds_read_b128 v[204:207], v143 offset:6144
	ds_read_b128 v[208:211], v143 offset:7168
	global_load_lds_dwordx4 v[138:139], off
	v_lshl_add_u64 v[138:139], s[20:21], 0, v[136:137]
	s_add_i32 m0, s19, 0xe000
	s_nop 0
	global_load_lds_dwordx4 v[138:139], off
	s_waitcnt vmcnt(8)
	s_waitcnt lgkmcnt(0)
	s_barrier
	s_setprio 1
	s_waitcnt lgkmcnt(0)
	v_mfma_f32_16x16x32_bf16 v[124:127], v[144:147], v[176:179], 0
	v_mfma_f32_16x16x32_bf16 v[120:123], v[152:155], v[176:179], 0
	v_mfma_f32_16x16x32_bf16 v[108:111], v[144:147], v[184:187], 0
	v_mfma_f32_16x16x32_bf16 v[104:107], v[152:155], v[184:187], 0
	v_mfma_f32_16x16x32_bf16 v[92:95], v[144:147], v[194:197], 0
	v_mfma_f32_16x16x32_bf16 v[88:91], v[152:155], v[194:197], 0
	v_mfma_f32_16x16x32_bf16 v[76:79], v[144:147], v[204:207], 0
	v_mfma_f32_16x16x32_bf16 v[72:75], v[152:155], v[204:207], 0
	v_mfma_f32_16x16x32_bf16 v[124:127], v[148:151], v[180:183], v[124:127]
	v_mfma_f32_16x16x32_bf16 v[120:123], v[156:159], v[180:183], v[120:123]
	v_mfma_f32_16x16x32_bf16 v[108:111], v[148:151], v[188:191], v[108:111]
	v_mfma_f32_16x16x32_bf16 v[104:107], v[156:159], v[188:191], v[104:107]
	v_mfma_f32_16x16x32_bf16 v[92:95], v[148:151], v[198:201], v[92:95]
	v_mfma_f32_16x16x32_bf16 v[88:91], v[156:159], v[198:201], v[88:91]
	v_mfma_f32_16x16x32_bf16 v[76:79], v[148:151], v[208:211], v[76:79]
	v_mfma_f32_16x16x32_bf16 v[72:75], v[156:159], v[208:211], v[72:75]
	s_setprio 0
	s_setprio 1
	v_mfma_f32_16x16x32_bf16 v[116:119], v[160:163], v[176:179], 0
	v_mfma_f32_16x16x32_bf16 v[112:115], v[168:171], v[176:179], 0
	v_mfma_f32_16x16x32_bf16 v[100:103], v[160:163], v[184:187], 0
	v_mfma_f32_16x16x32_bf16 v[96:99], v[168:171], v[184:187], 0
	v_mfma_f32_16x16x32_bf16 v[84:87], v[160:163], v[194:197], 0
	v_mfma_f32_16x16x32_bf16 v[80:83], v[168:171], v[194:197], 0
	v_mfma_f32_16x16x32_bf16 v[68:71], v[160:163], v[204:207], 0
	v_mfma_f32_16x16x32_bf16 v[64:67], v[168:171], v[204:207], 0
	v_mfma_f32_16x16x32_bf16 v[116:119], v[164:167], v[180:183], v[116:119]
	v_mfma_f32_16x16x32_bf16 v[112:115], v[172:175], v[180:183], v[112:115]
	v_mfma_f32_16x16x32_bf16 v[100:103], v[164:167], v[188:191], v[100:103]
	v_mfma_f32_16x16x32_bf16 v[96:99], v[172:175], v[188:191], v[96:99]
	v_mfma_f32_16x16x32_bf16 v[84:87], v[164:167], v[198:201], v[84:87]
	v_mfma_f32_16x16x32_bf16 v[80:83], v[172:175], v[198:201], v[80:83]
	v_mfma_f32_16x16x32_bf16 v[68:71], v[164:167], v[208:211], v[68:71]
	v_mfma_f32_16x16x32_bf16 v[64:67], v[172:175], v[208:211], v[64:67]
	s_setprio 0
	s_barrier
	s_add_i32 s43, s43, s35
	v_lshl_add_u64 v[138:139], s[22:23], 0, v[192:193]
	s_mov_b32 m0, s43
	ds_read_b128 v[176:179], v143 offset:16384
	ds_read_b128 v[180:183], v143 offset:17408
	ds_read_b128 v[184:187], v143 offset:18432
	ds_read_b128 v[188:191], v143 offset:19456
	ds_read_b128 v[194:197], v143 offset:20480
	ds_read_b128 v[198:201], v143 offset:21504
	ds_read_b128 v[204:207], v143 offset:22528
	ds_read_b128 v[208:211], v143 offset:23552
	global_load_lds_dwordx4 v[138:139], off
	s_add_i32 m0, s43, 0x2000
	s_add_u32 s76, s22, 0x40000
	v_lshl_add_u64 v[212:213], s[22:23], 0, v[128:129]
	s_addc_u32 s77, s23, 0
	s_add_i32 s43, s44, s35
	global_load_lds_dwordx4 v[212:213], off
	v_lshl_add_u64 v[214:215], s[76:77], 0, v[192:193]
	s_mov_b32 m0, s43
	v_lshl_add_u64 v[216:217], s[72:73], 0, v[130:131]
	global_load_lds_dwordx4 v[214:215], off
	v_lshl_add_u64 v[214:215], s[76:77], 0, v[128:129]
	s_add_i32 m0, s43, 0x2000
	s_nop 0
	global_load_lds_dwordx4 v[214:215], off
	v_lshl_add_u64 v[214:215], s[72:73], 0, v[132:133]
	s_mov_b32 m0, s19
	s_nop 0
	global_load_lds_dwordx4 v[214:215], off
	s_mov_b32 m0, s39
	s_nop 0
	global_load_lds_dwordx4 v[216:217], off
	s_waitcnt vmcnt(8)
	s_waitcnt lgkmcnt(0)
	s_barrier
; #define PG8_STAGE(bufoff, gbase, voff) do { _Pragma("unroll") for (int _i = 0; _i < 2; ++_i) \
;         __builtin_amdgcn_global_load_lds((const unsigned*)((const char*)(gbase) + (voff)[_i]), (LAS unsigned*)(lds + (bufoff) + ldsw + _i * 8192), 16, 0, 0); } while (0)
; #define PG8_LDA(dst, b, h) do { _Pragma("unroll") for (int m = 0; m < 4; ++m) _Pragma("unroll") for (int k = 0; k < 2; ++k) dst[m][k] = *(const LAS bf16x8*)(lds + PG8_SA(b, h) + aoff + m * 2048 + k * 1024); } while (0)
; #define PG8_LDB(dst, b, h) do { _Pragma("unroll") for (int n = 0; n < 2; ++n) _Pragma("unroll") for (int k = 0; k < 2; ++k) dst[n][k] = *(const LAS bf16x8*)(lds + PG8_SB(b, h) + boff + n * 2048 + k * 1024); } while (0)
; #define PG8_MMA(ai, bj, At, Bt) do { __builtin_amdgcn_s_setprio(1); _Pragma("unroll") for (int m = 0; m < 4; ++m) _Pragma("unroll") for (int n = 0; n < 2; ++n) _Pragma("unroll") for (int k = 0; k < 2; ++k) \
;         acc[ai][bj][m][n] = __builtin_amdgcn_mfma_f32_16x16x32_bf16(Bt[n][k], At[m][k], acc[ai][bj][m][n], 0, 0, 0); __builtin_amdgcn_s_setprio(0); } while (0)
; #define PG8_WAIT_V(n) asm volatile("s_waitcnt vmcnt(" #n ")" ::: "memory")
; #define PG8_WAIT_L(n) asm volatile("s_waitcnt lgkmcnt(" #n ")" ::: "memory")
; #define PG8_BAR __builtin_amdgcn_s_barrier()
; #define PG8_SCHED __builtin_amdgcn_sched_barrier(0)
; template <class Epi>
; __device__ __forceinline__ void gemm_phase(LAS unsigned char* lds, const Gemm g, const Sched& S, const Epi& E, const int tid) {
;     ...
;             PG8_WAIT_V(8); PG8_WAIT_L(0); PG8_BAR; PG8_MMA(1, 0, At, B0); PG8_MMA(1, 1, At, B1); PG8_BAR; PG8_SCHED;
;             PG8_LDB(B0, 1, 0); PG8_LDB(B1, 1, 1); PG8_SCHED; PG8_LDA(At, 1, 0); PG8_STAGE(PG8_SA(0, 1), a2 + hA, voffA);
;             PG8_WAIT_V(8); PG8_WAIT_L(0); PG8_BAR; PG8_MMA(0, 0, At, B0); PG8_MMA(0, 1, At, B1); PG8_BAR; PG8_SCHED;
	s_setprio 1
	s_waitcnt lgkmcnt(0)
	v_mfma_f32_16x16x32_bf16 v[60:63], v[144:147], v[176:179], 0
	v_mfma_f32_16x16x32_bf16 v[56:59], v[152:155], v[176:179], 0
	v_mfma_f32_16x16x32_bf16 v[44:47], v[144:147], v[184:187], 0
	v_mfma_f32_16x16x32_bf16 v[40:43], v[152:155], v[184:187], 0
	v_mfma_f32_16x16x32_bf16 v[28:31], v[144:147], v[194:197], 0
	v_mfma_f32_16x16x32_bf16 v[24:27], v[152:155], v[194:197], 0
	v_mfma_f32_16x16x32_bf16 v[12:15], v[144:147], v[204:207], 0
	v_mfma_f32_16x16x32_bf16 v[8:11], v[152:155], v[204:207], 0
	v_mfma_f32_16x16x32_bf16 v[60:63], v[148:151], v[180:183], v[60:63]
	v_mfma_f32_16x16x32_bf16 v[56:59], v[156:159], v[180:183], v[56:59]
	v_mfma_f32_16x16x32_bf16 v[44:47], v[148:151], v[188:191], v[44:47]
	v_mfma_f32_16x16x32_bf16 v[40:43], v[156:159], v[188:191], v[40:43]
	v_mfma_f32_16x16x32_bf16 v[28:31], v[148:151], v[198:201], v[28:31]
	v_mfma_f32_16x16x32_bf16 v[24:27], v[156:159], v[198:201], v[24:27]
	v_mfma_f32_16x16x32_bf16 v[12:15], v[148:151], v[208:211], v[12:15]
	v_mfma_f32_16x16x32_bf16 v[8:11], v[156:159], v[208:211], v[8:11]
	s_setprio 0
	s_setprio 1
	v_mfma_f32_16x16x32_bf16 v[52:55], v[160:163], v[176:179], 0
	v_mfma_f32_16x16x32_bf16 v[48:51], v[168:171], v[176:179], 0
	v_mfma_f32_16x16x32_bf16 v[36:39], v[160:163], v[184:187], 0
	v_mfma_f32_16x16x32_bf16 v[32:35], v[168:171], v[184:187], 0
	v_mfma_f32_16x16x32_bf16 v[20:23], v[160:163], v[194:197], 0
	v_mfma_f32_16x16x32_bf16 v[16:19], v[168:171], v[194:197], 0
	v_mfma_f32_16x16x32_bf16 v[4:7], v[160:163], v[204:207], 0
	v_mfma_f32_16x16x32_bf16 v[0:3], v[168:171], v[204:207], 0
	v_mfma_f32_16x16x32_bf16 v[52:55], v[164:167], v[180:183], v[52:55]
	v_mfma_f32_16x16x32_bf16 v[48:51], v[172:175], v[180:183], v[48:51]
	v_mfma_f32_16x16x32_bf16 v[36:39], v[164:167], v[188:191], v[36:39]
	v_mfma_f32_16x16x32_bf16 v[32:35], v[172:175], v[188:191], v[32:35]
	v_mfma_f32_16x16x32_bf16 v[20:23], v[164:167], v[198:201], v[20:23]
	v_mfma_f32_16x16x32_bf16 v[16:19], v[172:175], v[198:201], v[16:19]
	v_mfma_f32_16x16x32_bf16 v[4:7], v[164:167], v[208:211], v[4:7]
	v_mfma_f32_16x16x32_bf16 v[0:3], v[172:175], v[208:211], v[0:3]
	s_setprio 0
	s_barrier
	s_add_i32 s43, 0, 0x18000
	s_add_i32 s44, 0, 0x1c000
	v_add_u32_e32 v156, s43, v141
	v_add_u32_e32 v172, s44, v141
	ds_read_b128 v[144:147], v156
	ds_read_b128 v[148:151], v156 offset:1024
	ds_read_b128 v[152:155], v156 offset:2048
	ds_read_b128 v[156:159], v156 offset:3072
	ds_read_b128 v[160:163], v172
	ds_read_b128 v[164:167], v172 offset:1024
	ds_read_b128 v[168:171], v172 offset:2048
	ds_read_b128 v[172:175], v172 offset:3072
	s_add_u32 s72, s72, 0x40000
	s_addc_u32 s73, s73, 0
	s_mov_b32 m0, s40
	v_lshl_add_u64 v[218:219], s[72:73], 0, v[132:133]
	ds_read_b128 v[176:179], v143 offset:32768
	ds_read_b128 v[180:183], v143 offset:33792
	ds_read_b128 v[184:187], v143 offset:34816
	ds_read_b128 v[188:191], v143 offset:35840
	ds_read_b128 v[194:197], v143 offset:36864
	ds_read_b128 v[198:201], v143 offset:37888
	ds_read_b128 v[204:207], v143 offset:38912
	ds_read_b128 v[208:211], v143 offset:39936
	global_load_lds_dwordx4 v[218:219], off
	v_lshl_add_u64 v[218:219], s[72:73], 0, v[130:131]
	s_mov_b32 m0, s45
	s_nop 0
	global_load_lds_dwordx4 v[218:219], off
	s_waitcnt vmcnt(8)
	s_waitcnt lgkmcnt(0)
	s_barrier
	s_setprio 1
	s_waitcnt lgkmcnt(0)
	v_mfma_f32_16x16x32_bf16 v[124:127], v[144:147], v[176:179], v[124:127]
	v_mfma_f32_16x16x32_bf16 v[120:123], v[152:155], v[176:179], v[120:123]
	v_mfma_f32_16x16x32_bf16 v[108:111], v[144:147], v[184:187], v[108:111]
	v_mfma_f32_16x16x32_bf16 v[104:107], v[152:155], v[184:187], v[104:107]
	v_mfma_f32_16x16x32_bf16 v[92:95], v[144:147], v[194:197], v[92:95]
	v_mfma_f32_16x16x32_bf16 v[88:91], v[152:155], v[194:197], v[88:91]
	v_mfma_f32_16x16x32_bf16 v[76:79], v[144:147], v[204:207], v[76:79]
	v_mfma_f32_16x16x32_bf16 v[72:75], v[152:155], v[204:207], v[72:75]
	v_mfma_f32_16x16x32_bf16 v[124:127], v[148:151], v[180:183], v[124:127]
	v_mfma_f32_16x16x32_bf16 v[120:123], v[156:159], v[180:183], v[120:123]
	v_mfma_f32_16x16x32_bf16 v[108:111], v[148:151], v[188:191], v[108:111]
	v_mfma_f32_16x16x32_bf16 v[104:107], v[156:159], v[188:191], v[104:107]
	v_mfma_f32_16x16x32_bf16 v[92:95], v[148:151], v[198:201], v[92:95]
	v_mfma_f32_16x16x32_bf16 v[88:91], v[156:159], v[198:201], v[88:91]
	v_mfma_f32_16x16x32_bf16 v[76:79], v[148:151], v[208:211], v[76:79]
	v_mfma_f32_16x16x32_bf16 v[72:75], v[156:159], v[208:211], v[72:75]
	s_setprio 0
	s_setprio 1
	v_mfma_f32_16x16x32_bf16 v[116:119], v[160:163], v[176:179], v[116:119]
	v_mfma_f32_16x16x32_bf16 v[112:115], v[168:171], v[176:179], v[112:115]
	v_mfma_f32_16x16x32_bf16 v[100:103], v[160:163], v[184:187], v[100:103]
	v_mfma_f32_16x16x32_bf16 v[96:99], v[168:171], v[184:187], v[96:99]
	v_mfma_f32_16x16x32_bf16 v[84:87], v[160:163], v[194:197], v[84:87]
	v_mfma_f32_16x16x32_bf16 v[80:83], v[168:171], v[194:197], v[80:83]
	v_mfma_f32_16x16x32_bf16 v[68:71], v[160:163], v[204:207], v[68:71]
	v_mfma_f32_16x16x32_bf16 v[64:67], v[168:171], v[204:207], v[64:67]
	v_mfma_f32_16x16x32_bf16 v[116:119], v[164:167], v[180:183], v[116:119]
	v_mfma_f32_16x16x32_bf16 v[112:115], v[172:175], v[180:183], v[112:115]
	v_mfma_f32_16x16x32_bf16 v[100:103], v[164:167], v[188:191], v[100:103]
	v_mfma_f32_16x16x32_bf16 v[96:99], v[172:175], v[188:191], v[96:99]
	v_mfma_f32_16x16x32_bf16 v[84:87], v[164:167], v[198:201], v[84:87]
	v_mfma_f32_16x16x32_bf16 v[80:83], v[172:175], v[198:201], v[80:83]
	v_mfma_f32_16x16x32_bf16 v[68:71], v[164:167], v[208:211], v[68:71]
	v_mfma_f32_16x16x32_bf16 v[64:67], v[172:175], v[208:211], v[64:67]
	s_setprio 0
	s_barrier
; #define PG8_STAGE(bufoff, gbase, voff) do { _Pragma("unroll") for (int _i = 0; _i < 2; ++_i) \
;         __builtin_amdgcn_global_load_lds((const unsigned*)((const char*)(gbase) + (voff)[_i]), (LAS unsigned*)(lds + (bufoff) + ldsw + _i * 8192), 16, 0, 0); } while (0)
; #define PG8_LDA(dst, b, h) do { _Pragma("unroll") for (int m = 0; m < 4; ++m) _Pragma("unroll") for (int k = 0; k < 2; ++k) dst[m][k] = *(const LAS bf16x8*)(lds + PG8_SA(b, h) + aoff + m * 2048 + k * 1024); } while (0)
; #define PG8_MMA(ai, bj, At, Bt) do { __builtin_amdgcn_s_setprio(1); _Pragma("unroll") for (int m = 0; m < 4; ++m) _Pragma("unroll") for (int n = 0; n < 2; ++n) _Pragma("unroll") for (int k = 0; k < 2; ++k) \
;         acc[ai][bj][m][n] = __builtin_amdgcn_mfma_f32_16x16x32_bf16(Bt[n][k], At[m][k], acc[ai][bj][m][n], 0, 0, 0); __builtin_amdgcn_s_setprio(0); } while (0)
; #define PG8_WAIT_V(n) asm volatile("s_waitcnt vmcnt(" #n ")" ::: "memory")
; #define PG8_WAIT_L(n) asm volatile("s_waitcnt lgkmcnt(" #n ")" ::: "memory")
; #define PG8_BAR __builtin_amdgcn_s_barrier()
; #define PG8_SCHED __builtin_amdgcn_sched_barrier(0)
; template <class Epi>
; __device__ __forceinline__ void gemm_phase(LAS unsigned char* lds, const Gemm g, const Sched& S, const Epi& E, const int tid) {
;     ...
;             PG8_LDA(At, 1, 1); PG8_STAGE(PG8_SB(1, 0), b3, voffB); PG8_STAGE(PG8_SB(1, 1), b3 + hB, voffB); PG8_STAGE(PG8_SA(1, 0), a3, voffA);
;             PG8_WAIT_V(8); PG8_WAIT_L(0); PG8_BAR; PG8_MMA(1, 0, At, B0); PG8_MMA(1, 1, At, B1); PG8_BAR; PG8_SCHED;
;         }
	s_add_i32 s43, s43, s35
	v_lshl_add_u64 v[138:139], v[138:139], 0, s[94:95]
	s_mov_b32 m0, s43
	ds_read_b128 v[176:179], v143 offset:49152
	ds_read_b128 v[180:183], v143 offset:50176
	ds_read_b128 v[184:187], v143 offset:51200
	ds_read_b128 v[188:191], v143 offset:52224
	ds_read_b128 v[194:197], v143 offset:53248
	ds_read_b128 v[198:201], v143 offset:54272
	ds_read_b128 v[204:207], v143 offset:55296
	ds_read_b128 v[208:211], v143 offset:56320
	global_load_lds_dwordx4 v[138:139], off
	s_add_i32 m0, s43, 0x2000
	s_add_u32 s22, s22, 0x40080
	v_lshl_add_u64 v[138:139], v[212:213], 0, s[94:95]
	s_addc_u32 s23, s23, 0
	s_add_i32 s43, s44, s35
	global_load_lds_dwordx4 v[138:139], off
	v_lshl_add_u64 v[138:139], s[22:23], 0, v[192:193]
	s_mov_b32 m0, s43
	s_nop 0
	global_load_lds_dwordx4 v[138:139], off
	v_lshl_add_u64 v[138:139], s[22:23], 0, v[128:129]
	s_add_i32 m0, s43, 0x2000
	s_nop 0
	global_load_lds_dwordx4 v[138:139], off
	v_lshl_add_u64 v[138:139], v[214:215], 0, s[94:95]
	s_mov_b32 m0, s47
	s_nop 0
	global_load_lds_dwordx4 v[138:139], off
	v_lshl_add_u64 v[138:139], v[216:217], 0, s[94:95]
	s_mov_b32 m0, s51
	s_nop 0
	global_load_lds_dwordx4 v[138:139], off
	s_waitcnt vmcnt(8)
	s_waitcnt lgkmcnt(0)
	s_barrier
	s_setprio 1
	s_waitcnt lgkmcnt(0)
	v_mfma_f32_16x16x32_bf16 v[60:63], v[144:147], v[176:179], v[60:63]
	v_mfma_f32_16x16x32_bf16 v[56:59], v[152:155], v[176:179], v[56:59]
	v_mfma_f32_16x16x32_bf16 v[44:47], v[144:147], v[184:187], v[44:47]
	v_mfma_f32_16x16x32_bf16 v[40:43], v[152:155], v[184:187], v[40:43]
	v_mfma_f32_16x16x32_bf16 v[28:31], v[144:147], v[194:197], v[28:31]
	v_mfma_f32_16x16x32_bf16 v[24:27], v[152:155], v[194:197], v[24:27]
	v_mfma_f32_16x16x32_bf16 v[12:15], v[144:147], v[204:207], v[12:15]
	v_mfma_f32_16x16x32_bf16 v[8:11], v[152:155], v[204:207], v[8:11]
	v_mfma_f32_16x16x32_bf16 v[60:63], v[148:151], v[180:183], v[60:63]
	v_mfma_f32_16x16x32_bf16 v[56:59], v[156:159], v[180:183], v[56:59]
	v_mfma_f32_16x16x32_bf16 v[44:47], v[148:151], v[188:191], v[44:47]
	v_mfma_f32_16x16x32_bf16 v[40:43], v[156:159], v[188:191], v[40:43]
	v_mfma_f32_16x16x32_bf16 v[28:31], v[148:151], v[198:201], v[28:31]
	v_mfma_f32_16x16x32_bf16 v[24:27], v[156:159], v[198:201], v[24:27]
	v_mfma_f32_16x16x32_bf16 v[12:15], v[148:151], v[208:211], v[12:15]
	v_mfma_f32_16x16x32_bf16 v[8:11], v[156:159], v[208:211], v[8:11]
	s_setprio 0
	s_setprio 1
	v_mfma_f32_16x16x32_bf16 v[52:55], v[160:163], v[176:179], v[52:55]
	v_mfma_f32_16x16x32_bf16 v[48:51], v[168:171], v[176:179], v[48:51]
	v_mfma_f32_16x16x32_bf16 v[36:39], v[160:163], v[184:187], v[36:39]
	v_mfma_f32_16x16x32_bf16 v[32:35], v[168:171], v[184:187], v[32:35]
	v_mfma_f32_16x16x32_bf16 v[20:23], v[160:163], v[194:197], v[20:23]
	v_mfma_f32_16x16x32_bf16 v[16:19], v[168:171], v[194:197], v[16:19]
	v_mfma_f32_16x16x32_bf16 v[4:7], v[160:163], v[204:207], v[4:7]
	v_mfma_f32_16x16x32_bf16 v[0:3], v[168:171], v[204:207], v[0:3]
	v_mfma_f32_16x16x32_bf16 v[52:55], v[164:167], v[180:183], v[52:55]
	v_mfma_f32_16x16x32_bf16 v[48:51], v[172:175], v[180:183], v[48:51]
	v_mfma_f32_16x16x32_bf16 v[36:39], v[164:167], v[188:191], v[36:39]
	v_mfma_f32_16x16x32_bf16 v[32:35], v[172:175], v[188:191], v[32:35]
	v_mfma_f32_16x16x32_bf16 v[20:23], v[164:167], v[198:201], v[20:23]
	v_mfma_f32_16x16x32_bf16 v[16:19], v[172:175], v[198:201], v[16:19]
	v_mfma_f32_16x16x32_bf16 v[4:7], v[164:167], v[208:211], v[4:7]
	v_mfma_f32_16x16x32_bf16 v[0:3], v[172:175], v[208:211], v[0:3]
	s_setprio 0
	s_barrier
	s_add_i32 s42, s42, 2
	s_add_u32 s20, s20, 0x100
	s_addc_u32 s21, s21, 0
	s_add_u32 s13, s13, 0x100
	s_addc_u32 s15, s15, 0
	s_cmp_gt_u32 s42, 13
	s_cbranch_scc1 .Lgk_exit_4

; #define PG8_STAGE(bufoff, gbase, voff) do { _Pragma("unroll") for (int _i = 0; _i < 2; ++_i) \
;         __builtin_amdgcn_global_load_lds((const unsigned*)((const char*)(gbase) + (voff)[_i]), (LAS unsigned*)(lds + (bufoff) + ldsw + _i * 8192), 16, 0, 0); } while (0)
; #define PG8_LDA(dst, b, h) do { _Pragma("unroll") for (int m = 0; m < 4; ++m) _Pragma("unroll") for (int k = 0; k < 2; ++k) dst[m][k] = *(const LAS bf16x8*)(lds + PG8_SA(b, h) + aoff + m * 2048 + k * 1024); } while (0)
; #define PG8_LDB(dst, b, h) do { _Pragma("unroll") for (int n = 0; n < 2; ++n) _Pragma("unroll") for (int k = 0; k < 2; ++k) dst[n][k] = *(const LAS bf16x8*)(lds + PG8_SB(b, h) + boff + n * 2048 + k * 1024); } while (0)
; #define PG8_MMA(ai, bj, At, Bt) do { __builtin_amdgcn_s_setprio(1); _Pragma("unroll") for (int m = 0; m < 4; ++m) _Pragma("unroll") for (int n = 0; n < 2; ++n) _Pragma("unroll") for (int k = 0; k < 2; ++k) \
;         acc[ai][bj][m][n] = __builtin_amdgcn_mfma_f32_16x16x32_bf16(Bt[n][k], At[m][k], acc[ai][bj][m][n], 0, 0, 0); __builtin_amdgcn_s_setprio(0); } while (0)
; #define PG8_WAIT_V(n) asm volatile("s_waitcnt vmcnt(" #n ")" ::: "memory")
; #define PG8_WAIT_L(n) asm volatile("s_waitcnt lgkmcnt(" #n ")" ::: "memory")
; #define PG8_BAR __builtin_amdgcn_s_barrier()
; #define PG8_SCHED __builtin_amdgcn_sched_barrier(0)
; template <class Epi>
; __device__ __forceinline__ void gemm_phase(LAS unsigned char* lds, const Gemm g, const Sched& S, const Epi& E, const int tid) {
;     ...
;         for (int t = 0; t < nt; t += 2) {
;             const bool last = (t == nt - 2);
;             const char* a1 = cA + (size_t)(t + 1) * kstep;
;             const char* a2 = last ? nA : cA + (size_t)(t + 2) * kstep; const char* b2 = last ? nB : cB + (size_t)(t + 2) * kstep;
;             const char* a3 = a2 + kstep; const char* b3 = b2 + kstep;
;             PG8_LDB(B0, 0, 0); PG8_LDB(B1, 0, 1); PG8_SCHED; PG8_LDA(At, 0, 0); PG8_STAGE(PG8_SA(1, 1), a1 + hA, voffA);
;             PG8_WAIT_V(8); PG8_WAIT_L(0); PG8_BAR; PG8_MMA(0, 0, At, B0); PG8_MMA(0, 1, At, B1); PG8_BAR; PG8_SCHED;
;             PG8_LDA(At, 0, 1); PG8_STAGE(PG8_SB(0, 0), b2, voffB); PG8_STAGE(PG8_SB(0, 1), b2 + hB, voffB); PG8_STAGE(PG8_SA(0, 0), a2, voffA);
.LBB0_1410:
	s_add_u32 s80, s18, 0x100
	s_addc_u32 s81, s19, 0
	s_mov_b32 vcc_lo, -2
	s_add_u32 s18, s16, 0x100
	s_addc_u32 s19, s17, 0
	s_add_i32 s43, 0, 0x10000
	s_cmp_eq_u32 vcc_lo, 40
	s_cselect_b32 s23, s7, s19
	s_cselect_b32 s22, s6, s18
	s_cselect_b32 s21, s15, s81
	s_cselect_b32 s20, s14, s80
	s_add_i32 s44, 0, 0x14000
	v_add_u32_e32 v92, s43, v157
	v_add_u32_e32 v154, s44, v157
	ds_read_b128 v[64:67], v92
	ds_read_b128 v[68:71], v92 offset:1024
	ds_read_b128 v[80:83], v92 offset:2048
	ds_read_b128 v[92:95], v92 offset:3072
	ds_read_b128 v[160:163], v154
	ds_read_b128 v[164:167], v154 offset:1024
	ds_read_b128 v[168:171], v154 offset:2048
	ds_read_b128 v[172:175], v154 offset:3072
	v_lshl_add_u64 v[154:155], s[16:17], 0, v[150:151]
	s_add_i32 m0, s40, 0xc000
	ds_read_b128 v[176:179], v159
	ds_read_b128 v[180:183], v159 offset:1024
	ds_read_b128 v[184:187], v159 offset:2048
	ds_read_b128 v[188:191], v159 offset:3072
	ds_read_b128 v[194:197], v159 offset:4096
	ds_read_b128 v[198:201], v159 offset:5120
	ds_read_b128 v[204:207], v159 offset:6144
	ds_read_b128 v[208:211], v159 offset:7168
	global_load_lds_dwordx4 v[154:155], off
	v_lshl_add_u64 v[154:155], s[16:17], 0, v[152:153]
	s_add_i32 m0, s40, 0xe000
	s_nop 0
	global_load_lds_dwordx4 v[154:155], off
	s_waitcnt vmcnt(8)
	s_waitcnt lgkmcnt(0)
	s_barrier
	s_setprio 1
	s_waitcnt lgkmcnt(0)
	v_mfma_f32_16x16x32_bf16 v[140:143], v[64:67], v[176:179], 0
	v_mfma_f32_16x16x32_bf16 v[136:139], v[80:83], v[176:179], 0
	v_mfma_f32_16x16x32_bf16 v[132:135], v[64:67], v[184:187], 0
	v_mfma_f32_16x16x32_bf16 v[128:131], v[80:83], v[184:187], 0
	v_mfma_f32_16x16x32_bf16 v[108:111], v[64:67], v[194:197], 0
	v_mfma_f32_16x16x32_bf16 v[104:107], v[80:83], v[194:197], 0
	v_mfma_f32_16x16x32_bf16 v[100:103], v[64:67], v[204:207], 0
	v_mfma_f32_16x16x32_bf16 v[96:99], v[80:83], v[204:207], 0
	v_mfma_f32_16x16x32_bf16 v[140:143], v[68:71], v[180:183], v[140:143]
	v_mfma_f32_16x16x32_bf16 v[136:139], v[92:95], v[180:183], v[136:139]
	v_mfma_f32_16x16x32_bf16 v[132:135], v[68:71], v[188:191], v[132:135]
	v_mfma_f32_16x16x32_bf16 v[128:131], v[92:95], v[188:191], v[128:131]
	v_mfma_f32_16x16x32_bf16 v[108:111], v[68:71], v[198:201], v[108:111]
	v_mfma_f32_16x16x32_bf16 v[104:107], v[92:95], v[198:201], v[104:107]
	v_mfma_f32_16x16x32_bf16 v[100:103], v[68:71], v[208:211], v[100:103]
	v_mfma_f32_16x16x32_bf16 v[96:99], v[92:95], v[208:211], v[96:99]
	s_setprio 0
	s_setprio 1
	v_mfma_f32_16x16x32_bf16 v[124:127], v[160:163], v[176:179], 0
	v_mfma_f32_16x16x32_bf16 v[120:123], v[168:171], v[176:179], 0
	v_mfma_f32_16x16x32_bf16 v[116:119], v[160:163], v[184:187], 0
	v_mfma_f32_16x16x32_bf16 v[112:115], v[168:171], v[184:187], 0
	v_mfma_f32_16x16x32_bf16 v[88:91], v[160:163], v[194:197], 0
	v_mfma_f32_16x16x32_bf16 v[84:87], v[168:171], v[194:197], 0
	v_mfma_f32_16x16x32_bf16 v[76:79], v[160:163], v[204:207], 0
	v_mfma_f32_16x16x32_bf16 v[72:75], v[168:171], v[204:207], 0
	v_mfma_f32_16x16x32_bf16 v[124:127], v[164:167], v[180:183], v[124:127]
	v_mfma_f32_16x16x32_bf16 v[120:123], v[172:175], v[180:183], v[120:123]
	v_mfma_f32_16x16x32_bf16 v[116:119], v[164:167], v[188:191], v[116:119]
	v_mfma_f32_16x16x32_bf16 v[112:115], v[172:175], v[188:191], v[112:115]
	v_mfma_f32_16x16x32_bf16 v[88:91], v[164:167], v[198:201], v[88:91]
	v_mfma_f32_16x16x32_bf16 v[84:87], v[172:175], v[198:201], v[84:87]
	v_mfma_f32_16x16x32_bf16 v[76:79], v[164:167], v[208:211], v[76:79]
	v_mfma_f32_16x16x32_bf16 v[72:75], v[172:175], v[208:211], v[72:75]
	s_setprio 0
	s_barrier
	s_add_i32 s16, s43, s39
	v_lshl_add_u64 v[154:155], s[20:21], 0, v[192:193]
	s_mov_b32 m0, s16
	ds_read_b128 v[176:179], v159 offset:16384
	ds_read_b128 v[180:183], v159 offset:17408
	ds_read_b128 v[184:187], v159 offset:18432
	ds_read_b128 v[188:191], v159 offset:19456
	ds_read_b128 v[194:197], v159 offset:20480
	ds_read_b128 v[198:201], v159 offset:21504
	ds_read_b128 v[204:207], v159 offset:22528
	ds_read_b128 v[208:211], v159 offset:23552
	global_load_lds_dwordx4 v[154:155], off
	s_add_i32 m0, s16, 0x2000
	s_add_u32 s16, s20, 0xb0000
	v_lshl_add_u64 v[212:213], s[20:21], 0, v[144:145]
	s_addc_u32 s17, s21, 0
	s_add_i32 s43, s44, s39
	global_load_lds_dwordx4 v[212:213], off
	v_lshl_add_u64 v[214:215], s[16:17], 0, v[192:193]
	s_mov_b32 m0, s43
	v_lshl_add_u64 v[216:217], s[22:23], 0, v[146:147]
	global_load_lds_dwordx4 v[214:215], off
	v_lshl_add_u64 v[214:215], s[16:17], 0, v[144:145]
	s_add_i32 m0, s43, 0x2000
	s_nop 0
	global_load_lds_dwordx4 v[214:215], off
	v_lshl_add_u64 v[214:215], s[22:23], 0, v[148:149]
	s_mov_b32 m0, s40
	s_nop 0
	global_load_lds_dwordx4 v[214:215], off
	s_mov_b32 m0, s73
	s_nop 0
	global_load_lds_dwordx4 v[216:217], off
	s_waitcnt vmcnt(8)
	s_waitcnt lgkmcnt(0)
	s_barrier
; #define PG8_STAGE(bufoff, gbase, voff) do { _Pragma("unroll") for (int _i = 0; _i < 2; ++_i) \
;         __builtin_amdgcn_global_load_lds((const unsigned*)((const char*)(gbase) + (voff)[_i]), (LAS unsigned*)(lds + (bufoff) + ldsw + _i * 8192), 16, 0, 0); } while (0)
; #define PG8_LDA(dst, b, h) do { _Pragma("unroll") for (int m = 0; m < 4; ++m) _Pragma("unroll") for (int k = 0; k < 2; ++k) dst[m][k] = *(const LAS bf16x8*)(lds + PG8_SA(b, h) + aoff + m * 2048 + k * 1024); } while (0)
; #define PG8_LDB(dst, b, h) do { _Pragma("unroll") for (int n = 0; n < 2; ++n) _Pragma("unroll") for (int k = 0; k < 2; ++k) dst[n][k] = *(const LAS bf16x8*)(lds + PG8_SB(b, h) + boff + n * 2048 + k * 1024); } while (0)
; #define PG8_MMA(ai, bj, At, Bt) do { __builtin_amdgcn_s_setprio(1); _Pragma("unroll") for (int m = 0; m < 4; ++m) _Pragma("unroll") for (int n = 0; n < 2; ++n) _Pragma("unroll") for (int k = 0; k < 2; ++k) \
;         acc[ai][bj][m][n] = __builtin_amdgcn_mfma_f32_16x16x32_bf16(Bt[n][k], At[m][k], acc[ai][bj][m][n], 0, 0, 0); __builtin_amdgcn_s_setprio(0); } while (0)
; #define PG8_WAIT_V(n) asm volatile("s_waitcnt vmcnt(" #n ")" ::: "memory")
; #define PG8_WAIT_L(n) asm volatile("s_waitcnt lgkmcnt(" #n ")" ::: "memory")
; #define PG8_BAR __builtin_amdgcn_s_barrier()
; #define PG8_SCHED __builtin_amdgcn_sched_barrier(0)
; template <class Epi>
; __device__ __forceinline__ void gemm_phase(LAS unsigned char* lds, const Gemm g, const Sched& S, const Epi& E, const int tid) {
;     ...
;             PG8_WAIT_V(8); PG8_WAIT_L(0); PG8_BAR; PG8_MMA(1, 0, At, B0); PG8_MMA(1, 1, At, B1); PG8_BAR; PG8_SCHED;
;             PG8_LDB(B0, 1, 0); PG8_LDB(B1, 1, 1); PG8_SCHED; PG8_LDA(At, 1, 0); PG8_STAGE(PG8_SA(0, 1), a2 + hA, voffA);
;             PG8_WAIT_V(8); PG8_WAIT_L(0); PG8_BAR; PG8_MMA(0, 0, At, B0); PG8_MMA(0, 1, At, B1); PG8_BAR; PG8_SCHED;
	s_setprio 1
	s_waitcnt lgkmcnt(0)
	v_mfma_f32_16x16x32_bf16 v[60:63], v[64:67], v[176:179], 0
	v_mfma_f32_16x16x32_bf16 v[56:59], v[80:83], v[176:179], 0
	v_mfma_f32_16x16x32_bf16 v[52:55], v[64:67], v[184:187], 0
	v_mfma_f32_16x16x32_bf16 v[48:51], v[80:83], v[184:187], 0
	v_mfma_f32_16x16x32_bf16 v[28:31], v[64:67], v[194:197], 0
	v_mfma_f32_16x16x32_bf16 v[24:27], v[80:83], v[194:197], 0
	v_mfma_f32_16x16x32_bf16 v[16:19], v[64:67], v[204:207], 0
	v_mfma_f32_16x16x32_bf16 v[8:11], v[80:83], v[204:207], 0
	v_mfma_f32_16x16x32_bf16 v[60:63], v[68:71], v[180:183], v[60:63]
	v_mfma_f32_16x16x32_bf16 v[56:59], v[92:95], v[180:183], v[56:59]
	v_mfma_f32_16x16x32_bf16 v[52:55], v[68:71], v[188:191], v[52:55]
	v_mfma_f32_16x16x32_bf16 v[48:51], v[92:95], v[188:191], v[48:51]
	v_mfma_f32_16x16x32_bf16 v[28:31], v[68:71], v[198:201], v[28:31]
	v_mfma_f32_16x16x32_bf16 v[24:27], v[92:95], v[198:201], v[24:27]
	v_mfma_f32_16x16x32_bf16 v[16:19], v[68:71], v[208:211], v[16:19]
	v_mfma_f32_16x16x32_bf16 v[8:11], v[92:95], v[208:211], v[8:11]
	s_setprio 0
	s_setprio 1
	v_mfma_f32_16x16x32_bf16 v[44:47], v[160:163], v[176:179], 0
	v_mfma_f32_16x16x32_bf16 v[40:43], v[168:171], v[176:179], 0
	v_mfma_f32_16x16x32_bf16 v[36:39], v[160:163], v[184:187], 0
	v_mfma_f32_16x16x32_bf16 v[32:35], v[168:171], v[184:187], 0
	v_mfma_f32_16x16x32_bf16 v[20:23], v[160:163], v[194:197], 0
	v_mfma_f32_16x16x32_bf16 v[12:15], v[168:171], v[194:197], 0
	v_mfma_f32_16x16x32_bf16 v[4:7], v[160:163], v[204:207], 0
	v_mfma_f32_16x16x32_bf16 v[0:3], v[168:171], v[204:207], 0
	v_mfma_f32_16x16x32_bf16 v[44:47], v[164:167], v[180:183], v[44:47]
	v_mfma_f32_16x16x32_bf16 v[40:43], v[172:175], v[180:183], v[40:43]
	v_mfma_f32_16x16x32_bf16 v[36:39], v[164:167], v[188:191], v[36:39]
	v_mfma_f32_16x16x32_bf16 v[32:35], v[172:175], v[188:191], v[32:35]
	v_mfma_f32_16x16x32_bf16 v[20:23], v[164:167], v[198:201], v[20:23]
	v_mfma_f32_16x16x32_bf16 v[12:15], v[172:175], v[198:201], v[12:15]
	v_mfma_f32_16x16x32_bf16 v[4:7], v[164:167], v[208:211], v[4:7]
	v_mfma_f32_16x16x32_bf16 v[0:3], v[172:175], v[208:211], v[0:3]
	s_setprio 0
	s_barrier
	s_add_i32 s43, 0, 0x18000
	s_add_i32 s44, 0, 0x1c000
	v_add_u32_e32 v92, s43, v157
	v_add_u32_e32 v172, s44, v157
	ds_read_b128 v[64:67], v92
	ds_read_b128 v[68:71], v92 offset:1024
	ds_read_b128 v[80:83], v92 offset:2048
	ds_read_b128 v[92:95], v92 offset:3072
	ds_read_b128 v[160:163], v172
	ds_read_b128 v[164:167], v172 offset:1024
	ds_read_b128 v[168:171], v172 offset:2048
	ds_read_b128 v[172:175], v172 offset:3072
	s_add_u32 s16, s22, 0xb0000
	s_addc_u32 s17, s23, 0
	s_mov_b32 m0, s74
	v_lshl_add_u64 v[218:219], s[16:17], 0, v[148:149]
	ds_read_b128 v[176:179], v159 offset:32768
	ds_read_b128 v[180:183], v159 offset:33792
	ds_read_b128 v[184:187], v159 offset:34816
	ds_read_b128 v[188:191], v159 offset:35840
	ds_read_b128 v[194:197], v159 offset:36864
	ds_read_b128 v[198:201], v159 offset:37888
	ds_read_b128 v[204:207], v159 offset:38912
	ds_read_b128 v[208:211], v159 offset:39936
	global_load_lds_dwordx4 v[218:219], off
	v_lshl_add_u64 v[218:219], s[16:17], 0, v[146:147]
	s_mov_b32 m0, s75
	s_nop 0
	global_load_lds_dwordx4 v[218:219], off
	s_waitcnt vmcnt(8)
	s_waitcnt lgkmcnt(0)
	s_barrier
	s_setprio 1
	s_waitcnt lgkmcnt(0)
	v_mfma_f32_16x16x32_bf16 v[140:143], v[64:67], v[176:179], v[140:143]
	v_mfma_f32_16x16x32_bf16 v[136:139], v[80:83], v[176:179], v[136:139]
	v_mfma_f32_16x16x32_bf16 v[132:135], v[64:67], v[184:187], v[132:135]
	v_mfma_f32_16x16x32_bf16 v[128:131], v[80:83], v[184:187], v[128:131]
	v_mfma_f32_16x16x32_bf16 v[108:111], v[64:67], v[194:197], v[108:111]
	v_mfma_f32_16x16x32_bf16 v[104:107], v[80:83], v[194:197], v[104:107]
	v_mfma_f32_16x16x32_bf16 v[100:103], v[64:67], v[204:207], v[100:103]
	v_mfma_f32_16x16x32_bf16 v[96:99], v[80:83], v[204:207], v[96:99]
	v_mfma_f32_16x16x32_bf16 v[140:143], v[68:71], v[180:183], v[140:143]
	v_mfma_f32_16x16x32_bf16 v[136:139], v[92:95], v[180:183], v[136:139]
	v_mfma_f32_16x16x32_bf16 v[132:135], v[68:71], v[188:191], v[132:135]
	v_mfma_f32_16x16x32_bf16 v[128:131], v[92:95], v[188:191], v[128:131]
	v_mfma_f32_16x16x32_bf16 v[108:111], v[68:71], v[198:201], v[108:111]
	v_mfma_f32_16x16x32_bf16 v[104:107], v[92:95], v[198:201], v[104:107]
	v_mfma_f32_16x16x32_bf16 v[100:103], v[68:71], v[208:211], v[100:103]
	v_mfma_f32_16x16x32_bf16 v[96:99], v[92:95], v[208:211], v[96:99]
	s_setprio 0
	s_setprio 1
	v_mfma_f32_16x16x32_bf16 v[124:127], v[160:163], v[176:179], v[124:127]
	v_mfma_f32_16x16x32_bf16 v[120:123], v[168:171], v[176:179], v[120:123]
	v_mfma_f32_16x16x32_bf16 v[116:119], v[160:163], v[184:187], v[116:119]
	v_mfma_f32_16x16x32_bf16 v[112:115], v[168:171], v[184:187], v[112:115]
	v_mfma_f32_16x16x32_bf16 v[88:91], v[160:163], v[194:197], v[88:91]
	v_mfma_f32_16x16x32_bf16 v[84:87], v[168:171], v[194:197], v[84:87]
	v_mfma_f32_16x16x32_bf16 v[76:79], v[160:163], v[204:207], v[76:79]
	v_mfma_f32_16x16x32_bf16 v[72:75], v[168:171], v[204:207], v[72:75]
	v_mfma_f32_16x16x32_bf16 v[124:127], v[164:167], v[180:183], v[124:127]
	v_mfma_f32_16x16x32_bf16 v[120:123], v[172:175], v[180:183], v[120:123]
	v_mfma_f32_16x16x32_bf16 v[116:119], v[164:167], v[188:191], v[116:119]
	v_mfma_f32_16x16x32_bf16 v[112:115], v[172:175], v[188:191], v[112:115]
	v_mfma_f32_16x16x32_bf16 v[88:91], v[164:167], v[198:201], v[88:91]
	v_mfma_f32_16x16x32_bf16 v[84:87], v[172:175], v[198:201], v[84:87]
	v_mfma_f32_16x16x32_bf16 v[76:79], v[164:167], v[208:211], v[76:79]
	v_mfma_f32_16x16x32_bf16 v[72:75], v[172:175], v[208:211], v[72:75]
	s_setprio 0
	s_barrier
; #define PG8_STAGE(bufoff, gbase, voff) do { _Pragma("unroll") for (int _i = 0; _i < 2; ++_i) \
;         __builtin_amdgcn_global_load_lds((const unsigned*)((const char*)(gbase) + (voff)[_i]), (LAS unsigned*)(lds + (bufoff) + ldsw + _i * 8192), 16, 0, 0); } while (0)
; #define PG8_LDA(dst, b, h) do { _Pragma("unroll") for (int m = 0; m < 4; ++m) _Pragma("unroll") for (int k = 0; k < 2; ++k) dst[m][k] = *(const LAS bf16x8*)(lds + PG8_SA(b, h) + aoff + m * 2048 + k * 1024); } while (0)
; #define PG8_MMA(ai, bj, At, Bt) do { __builtin_amdgcn_s_setprio(1); _Pragma("unroll") for (int m = 0; m < 4; ++m) _Pragma("unroll") for (int n = 0; n < 2; ++n) _Pragma("unroll") for (int k = 0; k < 2; ++k) \
;         acc[ai][bj][m][n] = __builtin_amdgcn_mfma_f32_16x16x32_bf16(Bt[n][k], At[m][k], acc[ai][bj][m][n], 0, 0, 0); __builtin_amdgcn_s_setprio(0); } while (0)
; #define PG8_WAIT_V(n) asm volatile("s_waitcnt vmcnt(" #n ")" ::: "memory")
; #define PG8_WAIT_L(n) asm volatile("s_waitcnt lgkmcnt(" #n ")" ::: "memory")
; #define PG8_BAR __builtin_amdgcn_s_barrier()
; #define PG8_SCHED __builtin_amdgcn_sched_barrier(0)
; template <class Epi>
; __device__ __forceinline__ void gemm_phase(LAS unsigned char* lds, const Gemm g, const Sched& S, const Epi& E, const int tid) {
;     ...
;             PG8_LDA(At, 1, 1); PG8_STAGE(PG8_SB(1, 0), b3, voffB); PG8_STAGE(PG8_SB(1, 1), b3 + hB, voffB); PG8_STAGE(PG8_SA(1, 0), a3, voffA);
;             PG8_WAIT_V(8); PG8_WAIT_L(0); PG8_BAR; PG8_MMA(1, 0, At, B0); PG8_MMA(1, 1, At, B1); PG8_BAR; PG8_SCHED;
;         }
	s_add_i32 s16, s43, s39
	v_lshl_add_u64 v[154:155], v[154:155], 0, s[94:95]
	s_mov_b32 m0, s16
	ds_read_b128 v[176:179], v159 offset:49152
	ds_read_b128 v[180:183], v159 offset:50176
	ds_read_b128 v[184:187], v159 offset:51200
	ds_read_b128 v[188:191], v159 offset:52224
	ds_read_b128 v[194:197], v159 offset:53248
	ds_read_b128 v[198:201], v159 offset:54272
	ds_read_b128 v[204:207], v159 offset:55296
	ds_read_b128 v[208:211], v159 offset:56320
	global_load_lds_dwordx4 v[154:155], off
	s_add_i32 m0, s16, 0x2000
	s_add_u32 s16, s20, 0xb0080
	v_lshl_add_u64 v[154:155], v[212:213], 0, s[94:95]
	s_addc_u32 s17, s21, 0
	s_add_i32 s20, s44, s39
	global_load_lds_dwordx4 v[154:155], off
	v_lshl_add_u64 v[154:155], s[16:17], 0, v[192:193]
	s_mov_b32 m0, s20
	s_nop 0
	global_load_lds_dwordx4 v[154:155], off
	v_lshl_add_u64 v[154:155], s[16:17], 0, v[144:145]
	s_add_i32 m0, s20, 0x2000
	s_nop 0
	global_load_lds_dwordx4 v[154:155], off
	v_lshl_add_u64 v[154:155], v[214:215], 0, s[94:95]
	s_mov_b32 m0, s51
	s_nop 0
	global_load_lds_dwordx4 v[154:155], off
	v_lshl_add_u64 v[154:155], v[216:217], 0, s[94:95]
	s_mov_b32 m0, s76
	s_nop 0
	global_load_lds_dwordx4 v[154:155], off
	s_waitcnt vmcnt(8)
	s_waitcnt lgkmcnt(0)
	s_barrier
	s_setprio 1
	s_waitcnt lgkmcnt(0)
	v_mfma_f32_16x16x32_bf16 v[60:63], v[64:67], v[176:179], v[60:63]
	v_mfma_f32_16x16x32_bf16 v[56:59], v[80:83], v[176:179], v[56:59]
	v_mfma_f32_16x16x32_bf16 v[52:55], v[64:67], v[184:187], v[52:55]
	v_mfma_f32_16x16x32_bf16 v[48:51], v[80:83], v[184:187], v[48:51]
	v_mfma_f32_16x16x32_bf16 v[28:31], v[64:67], v[194:197], v[28:31]
	v_mfma_f32_16x16x32_bf16 v[24:27], v[80:83], v[194:197], v[24:27]
	v_mfma_f32_16x16x32_bf16 v[16:19], v[64:67], v[204:207], v[16:19]
	v_mfma_f32_16x16x32_bf16 v[8:11], v[80:83], v[204:207], v[8:11]
	v_mfma_f32_16x16x32_bf16 v[60:63], v[68:71], v[180:183], v[60:63]
	v_mfma_f32_16x16x32_bf16 v[56:59], v[92:95], v[180:183], v[56:59]
	v_mfma_f32_16x16x32_bf16 v[52:55], v[68:71], v[188:191], v[52:55]
	v_mfma_f32_16x16x32_bf16 v[48:51], v[92:95], v[188:191], v[48:51]
	v_mfma_f32_16x16x32_bf16 v[28:31], v[68:71], v[198:201], v[28:31]
	v_mfma_f32_16x16x32_bf16 v[24:27], v[92:95], v[198:201], v[24:27]
	v_mfma_f32_16x16x32_bf16 v[16:19], v[68:71], v[208:211], v[16:19]
	v_mfma_f32_16x16x32_bf16 v[8:11], v[92:95], v[208:211], v[8:11]
	s_setprio 0
	s_setprio 1
	v_mfma_f32_16x16x32_bf16 v[44:47], v[160:163], v[176:179], v[44:47]
	v_mfma_f32_16x16x32_bf16 v[40:43], v[168:171], v[176:179], v[40:43]
	v_mfma_f32_16x16x32_bf16 v[36:39], v[160:163], v[184:187], v[36:39]
	v_mfma_f32_16x16x32_bf16 v[32:35], v[168:171], v[184:187], v[32:35]
	v_mfma_f32_16x16x32_bf16 v[20:23], v[160:163], v[194:197], v[20:23]
	v_mfma_f32_16x16x32_bf16 v[12:15], v[168:171], v[194:197], v[12:15]
	v_mfma_f32_16x16x32_bf16 v[4:7], v[160:163], v[204:207], v[4:7]
	v_mfma_f32_16x16x32_bf16 v[0:3], v[168:171], v[204:207], v[0:3]
	v_mfma_f32_16x16x32_bf16 v[44:47], v[164:167], v[180:183], v[44:47]
	v_mfma_f32_16x16x32_bf16 v[40:43], v[172:175], v[180:183], v[40:43]
	v_mfma_f32_16x16x32_bf16 v[36:39], v[164:167], v[188:191], v[36:39]
	v_mfma_f32_16x16x32_bf16 v[32:35], v[172:175], v[188:191], v[32:35]
	v_mfma_f32_16x16x32_bf16 v[20:23], v[164:167], v[198:201], v[20:23]
	v_mfma_f32_16x16x32_bf16 v[12:15], v[172:175], v[198:201], v[12:15]
	v_mfma_f32_16x16x32_bf16 v[4:7], v[164:167], v[208:211], v[4:7]
	v_mfma_f32_16x16x32_bf16 v[0:3], v[172:175], v[208:211], v[0:3]
	s_setprio 0
	s_barrier
	s_add_i32 vcc_lo, vcc_lo, 2
	s_add_u32 s80, s80, 0x100
	s_addc_u32 s81, s81, 0
	s_cmp_gt_u32 vcc_lo, 41
	s_mov_b64 s[16:17], s[18:19]
	s_cbranch_scc1 .Lgk_exit_5

; #define PG8_BAR __builtin_amdgcn_s_barrier()
; template <class Epi>
; __device__ __forceinline__ void gemm_phase(LAS unsigned char* lds, const Gemm g, const Sched& S, const Epi& E, const int tid) {
;     ...
;         if (wr == 0) PG8_BAR;
.Lgk_exit_5:
	s_and_b64 vcc, exec, s[12:13]
	s_cbranch_vccz .LBB0_1414
	s_barrier
